# P1/P8 row passes: a wave owns 16 consecutive rows, so g/shift/scale are loaded once per wave and each row needs only its 4 x loads (2 rows ahead, exact counted waits)
# speedup vs baseline: 1.0074x; 1.0074x over previous
.Lp1_begin2:
	v_mbcnt_lo_u32_b32 v0, -1, 0
	v_mbcnt_hi_u32_b32 v0, -1, v0
	v_and_b32_e32 v0, 63, v0
	v_readlane_b32 s1, v254, 21
	v_readlane_b32 s16, v254, 3
	v_readlane_b32 s17, v254, 4
	v_readlane_b32 s26, v254, 13
	v_readlane_b32 s27, v254, 14
	s_ashr_i32 s53, s52, 31
	v_lshlrev_b32_e32 v1, 4, v0
	v_lshlrev_b32_e32 v2, 3, v0
	v_mov_b32_e32 v3, 0x358637bd
	v_add_u32_e32 v4, 0x1000, v1
	s_lshl_b32 s1, s1, 4
	global_load_dwordx4 v[10:13], v1, s[26:27]
	global_load_dwordx4 v[14:17], v1, s[26:27] offset:1024
	global_load_dwordx4 v[18:21], v1, s[26:27] offset:2048
	global_load_dwordx4 v[22:25], v1, s[26:27] offset:3072
	s_lshl_b32 s0, s1, 12
	s_add_u32 s4, s16, s0
	s_addc_u32 s5, s17, 0
	s_ashr_i32 s0, s1, 12
	s_mul_i32 s0, s0, 0x6000
	s_add_u32 s6, s82, s0
	s_addc_u32 s7, s83, 0
	s_lshl_b32 s0, s1, 11
	s_add_u32 s8, s82, 0x3000000
	s_addc_u32 s9, s83, 0
	s_add_u32 s8, s8, s0
	s_addc_u32 s9, s9, 0
	global_load_dwordx4 v[26:29], v1, s[4:5] nt
	global_load_dwordx4 v[30:33], v1, s[4:5] offset:1024 nt
	global_load_dwordx4 v[34:37], v1, s[4:5] offset:2048 nt
	global_load_dwordx4 v[38:41], v1, s[4:5] offset:3072 nt
	s_add_u32 s4, s4, 0x1000
	s_addc_u32 s5, s5, 0
	global_load_dwordx4 v[58:61], v1, s[6:7]
	global_load_dwordx4 v[62:65], v1, s[6:7] offset:1024
	global_load_dwordx4 v[66:69], v1, s[6:7] offset:2048
	global_load_dwordx4 v[70:73], v1, s[6:7] offset:3072
	global_load_dwordx4 v[74:77], v4, s[6:7]
	global_load_dwordx4 v[78:81], v4, s[6:7] offset:1024
	global_load_dwordx4 v[82:85], v4, s[6:7] offset:2048
	global_load_dwordx4 v[86:89], v4, s[6:7] offset:3072
	global_load_dwordx4 v[42:45], v1, s[4:5] nt
	global_load_dwordx4 v[46:49], v1, s[4:5] offset:1024 nt
	global_load_dwordx4 v[50:53], v1, s[4:5] offset:2048 nt
	global_load_dwordx4 v[54:57], v1, s[4:5] offset:3072 nt
	s_add_u32 s4, s4, 0x1000
	s_addc_u32 s5, s5, 0
	global_load_dwordx4 v[90:93], v1, s[4:5] nt
	global_load_dwordx4 v[94:97], v1, s[4:5] offset:1024 nt
	global_load_dwordx4 v[98:101], v1, s[4:5] offset:2048 nt
	global_load_dwordx4 v[102:105], v1, s[4:5] offset:3072 nt
	s_add_u32 s4, s4, 0x1000
	s_addc_u32 s5, s5, 0
	s_waitcnt vmcnt(8)
	v_pk_add_f32 v[74:75], v[74:75], 1.0 op_sel_hi:[1,0]
	v_pk_add_f32 v[76:77], v[76:77], 1.0 op_sel_hi:[1,0]
	v_pk_add_f32 v[78:79], v[78:79], 1.0 op_sel_hi:[1,0]
	v_pk_add_f32 v[80:81], v[80:81], 1.0 op_sel_hi:[1,0]
	v_pk_add_f32 v[82:83], v[82:83], 1.0 op_sel_hi:[1,0]
	v_pk_add_f32 v[84:85], v[84:85], 1.0 op_sel_hi:[1,0]
	v_pk_add_f32 v[86:87], v[86:87], 1.0 op_sel_hi:[1,0]
	v_pk_add_f32 v[88:89], v[88:89], 1.0 op_sel_hi:[1,0]
	v_mul_f32_e32 v122, v26, v26
	v_fmac_f32_e32 v122, v27, v27
	v_fmac_f32_e32 v122, v28, v28
	v_fmac_f32_e32 v122, v29, v29
	v_mul_f32_e32 v123, v30, v30
	v_fmac_f32_e32 v123, v31, v31
	v_fmac_f32_e32 v123, v32, v32
	v_fmac_f32_e32 v123, v33, v33
	v_mul_f32_e32 v124, v34, v34
	v_fmac_f32_e32 v124, v35, v35
	v_fmac_f32_e32 v124, v36, v36
	v_fmac_f32_e32 v124, v37, v37
	v_mul_f32_e32 v125, v38, v38
	v_fmac_f32_e32 v125, v39, v39
	v_fmac_f32_e32 v125, v40, v40
	v_fmac_f32_e32 v125, v41, v41
	v_add_f32_e32 v122, v122, v123
	v_add_f32_e32 v124, v124, v125
	v_add_f32_e32 v122, v122, v124
	s_nop 1
	v_add_f32_dpp v122, v122, v122 quad_perm:[1,0,3,2] row_mask:0xf bank_mask:0xf bound_ctrl:1
	s_nop 1
	v_add_f32_dpp v122, v122, v122 quad_perm:[2,3,0,1] row_mask:0xf bank_mask:0xf bound_ctrl:1
	s_nop 1
	v_add_f32_dpp v122, v122, v122 row_half_mirror row_mask:0xf bank_mask:0xf bound_ctrl:1
	s_nop 1
	v_add_f32_dpp v122, v122, v122 row_mirror row_mask:0xf bank_mask:0xf bound_ctrl:1
	v_mov_b32_e32 v123, v122
	s_nop 1
	v_permlane16_swap_b32_e32 v122, v123
	v_add_f32_e32 v122, v122, v123
	v_mov_b32_e32 v123, v122
	s_nop 1
	v_permlane32_swap_b32_e32 v122, v123
	v_add_f32_e32 v122, v122, v123
	v_fmamk_f32 v122, v122, 0x3a800000, v3
	v_rsq_f32_e32 v122, v122
	s_nop 0
	v_mov_b32_e32 v123, v122
	v_pk_mul_f32 v[26:27], v[122:123], v[26:27]
	v_pk_mul_f32 v[26:27], v[10:11], v[26:27]
	v_pk_fma_f32 v[26:27], v[74:75], v[26:27], v[58:59]
	v_pk_mul_f32 v[28:29], v[122:123], v[28:29]
	v_pk_mul_f32 v[28:29], v[12:13], v[28:29]
	v_pk_fma_f32 v[28:29], v[76:77], v[28:29], v[60:61]
	v_cvt_pk_bf16_f32 v124, v26, v27
	v_cvt_pk_bf16_f32 v125, v28, v29
	global_store_dwordx2 v2, v[124:125], s[8:9]
	v_pk_mul_f32 v[30:31], v[122:123], v[30:31]
	v_pk_mul_f32 v[30:31], v[14:15], v[30:31]
	v_pk_fma_f32 v[30:31], v[78:79], v[30:31], v[62:63]
	v_pk_mul_f32 v[32:33], v[122:123], v[32:33]
	v_pk_mul_f32 v[32:33], v[16:17], v[32:33]
	v_pk_fma_f32 v[32:33], v[80:81], v[32:33], v[64:65]
	v_cvt_pk_bf16_f32 v126, v30, v31
	v_cvt_pk_bf16_f32 v127, v32, v33
	global_store_dwordx2 v2, v[126:127], s[8:9] offset:512
	v_pk_mul_f32 v[34:35], v[122:123], v[34:35]
	v_pk_mul_f32 v[34:35], v[18:19], v[34:35]
	v_pk_fma_f32 v[34:35], v[82:83], v[34:35], v[66:67]
	v_pk_mul_f32 v[36:37], v[122:123], v[36:37]
	v_pk_mul_f32 v[36:37], v[20:21], v[36:37]
	v_pk_fma_f32 v[36:37], v[84:85], v[36:37], v[68:69]
	v_cvt_pk_bf16_f32 v124, v34, v35
	v_cvt_pk_bf16_f32 v125, v36, v37
	global_store_dwordx2 v2, v[124:125], s[8:9] offset:1024
	v_pk_mul_f32 v[38:39], v[122:123], v[38:39]
	v_pk_mul_f32 v[38:39], v[22:23], v[38:39]
	v_pk_fma_f32 v[38:39], v[86:87], v[38:39], v[70:71]
	v_pk_mul_f32 v[40:41], v[122:123], v[40:41]
	v_pk_mul_f32 v[40:41], v[24:25], v[40:41]
	v_pk_fma_f32 v[40:41], v[88:89], v[40:41], v[72:73]
	v_cvt_pk_bf16_f32 v126, v38, v39
	v_cvt_pk_bf16_f32 v127, v40, v41
	global_store_dwordx2 v2, v[126:127], s[8:9] offset:1536
	s_add_u32 s8, s8, 0x800
	s_addc_u32 s9, s9, 0
	global_load_dwordx4 v[26:29], v1, s[4:5] nt
	global_load_dwordx4 v[30:33], v1, s[4:5] offset:1024 nt
	global_load_dwordx4 v[34:37], v1, s[4:5] offset:2048 nt
	global_load_dwordx4 v[38:41], v1, s[4:5] offset:3072 nt
	s_add_u32 s4, s4, 0x1000
	s_addc_u32 s5, s5, 0
	s_waitcnt vmcnt(12)
	v_mul_f32_e32 v122, v42, v42
	v_fmac_f32_e32 v122, v43, v43
	v_fmac_f32_e32 v122, v44, v44
	v_fmac_f32_e32 v122, v45, v45
	v_mul_f32_e32 v123, v46, v46
	v_fmac_f32_e32 v123, v47, v47
	v_fmac_f32_e32 v123, v48, v48
	v_fmac_f32_e32 v123, v49, v49
	v_mul_f32_e32 v124, v50, v50
	v_fmac_f32_e32 v124, v51, v51
	v_fmac_f32_e32 v124, v52, v52
	v_fmac_f32_e32 v124, v53, v53
	v_mul_f32_e32 v125, v54, v54
	v_fmac_f32_e32 v125, v55, v55
	v_fmac_f32_e32 v125, v56, v56
	v_fmac_f32_e32 v125, v57, v57
	v_add_f32_e32 v122, v122, v123
	v_add_f32_e32 v124, v124, v125
	v_add_f32_e32 v122, v122, v124
	s_nop 1
	v_add_f32_dpp v122, v122, v122 quad_perm:[1,0,3,2] row_mask:0xf bank_mask:0xf bound_ctrl:1
	s_nop 1
	v_add_f32_dpp v122, v122, v122 quad_perm:[2,3,0,1] row_mask:0xf bank_mask:0xf bound_ctrl:1
	s_nop 1
	v_add_f32_dpp v122, v122, v122 row_half_mirror row_mask:0xf bank_mask:0xf bound_ctrl:1
	s_nop 1
	v_add_f32_dpp v122, v122, v122 row_mirror row_mask:0xf bank_mask:0xf bound_ctrl:1
	v_mov_b32_e32 v123, v122
	s_nop 1
	v_permlane16_swap_b32_e32 v122, v123
	v_add_f32_e32 v122, v122, v123
	v_mov_b32_e32 v123, v122
	s_nop 1
	v_permlane32_swap_b32_e32 v122, v123
	v_add_f32_e32 v122, v122, v123
	v_fmamk_f32 v122, v122, 0x3a800000, v3
	v_rsq_f32_e32 v122, v122
	s_nop 0
	v_mov_b32_e32 v123, v122
	v_pk_mul_f32 v[42:43], v[122:123], v[42:43]
	v_pk_mul_f32 v[42:43], v[10:11], v[42:43]
	v_pk_fma_f32 v[42:43], v[74:75], v[42:43], v[58:59]
	v_pk_mul_f32 v[44:45], v[122:123], v[44:45]
	v_pk_mul_f32 v[44:45], v[12:13], v[44:45]
	v_pk_fma_f32 v[44:45], v[76:77], v[44:45], v[60:61]
	v_cvt_pk_bf16_f32 v124, v42, v43
	v_cvt_pk_bf16_f32 v125, v44, v45
	global_store_dwordx2 v2, v[124:125], s[8:9]
	v_pk_mul_f32 v[46:47], v[122:123], v[46:47]
	v_pk_mul_f32 v[46:47], v[14:15], v[46:47]
	v_pk_fma_f32 v[46:47], v[78:79], v[46:47], v[62:63]
	v_pk_mul_f32 v[48:49], v[122:123], v[48:49]
	v_pk_mul_f32 v[48:49], v[16:17], v[48:49]
	v_pk_fma_f32 v[48:49], v[80:81], v[48:49], v[64:65]
	v_cvt_pk_bf16_f32 v126, v46, v47
	v_cvt_pk_bf16_f32 v127, v48, v49
	global_store_dwordx2 v2, v[126:127], s[8:9] offset:512
	v_pk_mul_f32 v[50:51], v[122:123], v[50:51]
	v_pk_mul_f32 v[50:51], v[18:19], v[50:51]
	v_pk_fma_f32 v[50:51], v[82:83], v[50:51], v[66:67]
	v_pk_mul_f32 v[52:53], v[122:123], v[52:53]
	v_pk_mul_f32 v[52:53], v[20:21], v[52:53]
	v_pk_fma_f32 v[52:53], v[84:85], v[52:53], v[68:69]
	v_cvt_pk_bf16_f32 v124, v50, v51
	v_cvt_pk_bf16_f32 v125, v52, v53
	global_store_dwordx2 v2, v[124:125], s[8:9] offset:1024
	v_pk_mul_f32 v[54:55], v[122:123], v[54:55]
	v_pk_mul_f32 v[54:55], v[22:23], v[54:55]
	v_pk_fma_f32 v[54:55], v[86:87], v[54:55], v[70:71]
	v_pk_mul_f32 v[56:57], v[122:123], v[56:57]
	v_pk_mul_f32 v[56:57], v[24:25], v[56:57]
	v_pk_fma_f32 v[56:57], v[88:89], v[56:57], v[72:73]
	v_cvt_pk_bf16_f32 v126, v54, v55
	v_cvt_pk_bf16_f32 v127, v56, v57
	global_store_dwordx2 v2, v[126:127], s[8:9] offset:1536
	s_add_u32 s8, s8, 0x800
	s_addc_u32 s9, s9, 0
	global_load_dwordx4 v[42:45], v1, s[4:5] nt
	global_load_dwordx4 v[46:49], v1, s[4:5] offset:1024 nt
	global_load_dwordx4 v[50:53], v1, s[4:5] offset:2048 nt
	global_load_dwordx4 v[54:57], v1, s[4:5] offset:3072 nt
	s_add_u32 s4, s4, 0x1000
	s_addc_u32 s5, s5, 0
	s_waitcnt vmcnt(16)
	v_mul_f32_e32 v122, v90, v90
	v_fmac_f32_e32 v122, v91, v91
	v_fmac_f32_e32 v122, v92, v92
	v_fmac_f32_e32 v122, v93, v93
	v_mul_f32_e32 v123, v94, v94
	v_fmac_f32_e32 v123, v95, v95
	v_fmac_f32_e32 v123, v96, v96
	v_fmac_f32_e32 v123, v97, v97
	v_mul_f32_e32 v124, v98, v98
	v_fmac_f32_e32 v124, v99, v99
	v_fmac_f32_e32 v124, v100, v100
	v_fmac_f32_e32 v124, v101, v101
	v_mul_f32_e32 v125, v102, v102
	v_fmac_f32_e32 v125, v103, v103
	v_fmac_f32_e32 v125, v104, v104
	v_fmac_f32_e32 v125, v105, v105
	v_add_f32_e32 v122, v122, v123
	v_add_f32_e32 v124, v124, v125
	v_add_f32_e32 v122, v122, v124
	s_nop 1
	v_add_f32_dpp v122, v122, v122 quad_perm:[1,0,3,2] row_mask:0xf bank_mask:0xf bound_ctrl:1
	s_nop 1
	v_add_f32_dpp v122, v122, v122 quad_perm:[2,3,0,1] row_mask:0xf bank_mask:0xf bound_ctrl:1
	s_nop 1
	v_add_f32_dpp v122, v122, v122 row_half_mirror row_mask:0xf bank_mask:0xf bound_ctrl:1
	s_nop 1
	v_add_f32_dpp v122, v122, v122 row_mirror row_mask:0xf bank_mask:0xf bound_ctrl:1
	v_mov_b32_e32 v123, v122
	s_nop 1
	v_permlane16_swap_b32_e32 v122, v123
	v_add_f32_e32 v122, v122, v123
	v_mov_b32_e32 v123, v122
	s_nop 1
	v_permlane32_swap_b32_e32 v122, v123
	v_add_f32_e32 v122, v122, v123
	v_fmamk_f32 v122, v122, 0x3a800000, v3
	v_rsq_f32_e32 v122, v122
	s_nop 0
	v_mov_b32_e32 v123, v122
	v_pk_mul_f32 v[90:91], v[122:123], v[90:91]
	v_pk_mul_f32 v[90:91], v[10:11], v[90:91]
	v_pk_fma_f32 v[90:91], v[74:75], v[90:91], v[58:59]
	v_pk_mul_f32 v[92:93], v[122:123], v[92:93]
	v_pk_mul_f32 v[92:93], v[12:13], v[92:93]
	v_pk_fma_f32 v[92:93], v[76:77], v[92:93], v[60:61]
	v_cvt_pk_bf16_f32 v124, v90, v91
	v_cvt_pk_bf16_f32 v125, v92, v93
	global_store_dwordx2 v2, v[124:125], s[8:9]
	v_pk_mul_f32 v[94:95], v[122:123], v[94:95]
	v_pk_mul_f32 v[94:95], v[14:15], v[94:95]
	v_pk_fma_f32 v[94:95], v[78:79], v[94:95], v[62:63]
	v_pk_mul_f32 v[96:97], v[122:123], v[96:97]
	v_pk_mul_f32 v[96:97], v[16:17], v[96:97]
	v_pk_fma_f32 v[96:97], v[80:81], v[96:97], v[64:65]
	v_cvt_pk_bf16_f32 v126, v94, v95
	v_cvt_pk_bf16_f32 v127, v96, v97
	global_store_dwordx2 v2, v[126:127], s[8:9] offset:512
	v_pk_mul_f32 v[98:99], v[122:123], v[98:99]
	v_pk_mul_f32 v[98:99], v[18:19], v[98:99]
	v_pk_fma_f32 v[98:99], v[82:83], v[98:99], v[66:67]
	v_pk_mul_f32 v[100:101], v[122:123], v[100:101]
	v_pk_mul_f32 v[100:101], v[20:21], v[100:101]
	v_pk_fma_f32 v[100:101], v[84:85], v[100:101], v[68:69]
	v_cvt_pk_bf16_f32 v124, v98, v99
	v_cvt_pk_bf16_f32 v125, v100, v101
	global_store_dwordx2 v2, v[124:125], s[8:9] offset:1024
	v_pk_mul_f32 v[102:103], v[122:123], v[102:103]
	v_pk_mul_f32 v[102:103], v[22:23], v[102:103]
	v_pk_fma_f32 v[102:103], v[86:87], v[102:103], v[70:71]
	v_pk_mul_f32 v[104:105], v[122:123], v[104:105]
	v_pk_mul_f32 v[104:105], v[24:25], v[104:105]
	v_pk_fma_f32 v[104:105], v[88:89], v[104:105], v[72:73]
	v_cvt_pk_bf16_f32 v126, v102, v103
	v_cvt_pk_bf16_f32 v127, v104, v105
	global_store_dwordx2 v2, v[126:127], s[8:9] offset:1536
	s_add_u32 s8, s8, 0x800
	s_addc_u32 s9, s9, 0
	global_load_dwordx4 v[90:93], v1, s[4:5] nt
	global_load_dwordx4 v[94:97], v1, s[4:5] offset:1024 nt
	global_load_dwordx4 v[98:101], v1, s[4:5] offset:2048 nt
	global_load_dwordx4 v[102:105], v1, s[4:5] offset:3072 nt
	s_add_u32 s4, s4, 0x1000
	s_addc_u32 s5, s5, 0
	s_waitcnt vmcnt(16)
	v_mul_f32_e32 v122, v26, v26
	v_fmac_f32_e32 v122, v27, v27
	v_fmac_f32_e32 v122, v28, v28
	v_fmac_f32_e32 v122, v29, v29
	v_mul_f32_e32 v123, v30, v30
	v_fmac_f32_e32 v123, v31, v31
	v_fmac_f32_e32 v123, v32, v32
	v_fmac_f32_e32 v123, v33, v33
	v_mul_f32_e32 v124, v34, v34
	v_fmac_f32_e32 v124, v35, v35
	v_fmac_f32_e32 v124, v36, v36
	v_fmac_f32_e32 v124, v37, v37
	v_mul_f32_e32 v125, v38, v38
	v_fmac_f32_e32 v125, v39, v39
	v_fmac_f32_e32 v125, v40, v40
	v_fmac_f32_e32 v125, v41, v41
	v_add_f32_e32 v122, v122, v123
	v_add_f32_e32 v124, v124, v125
	v_add_f32_e32 v122, v122, v124
	s_nop 1
	v_add_f32_dpp v122, v122, v122 quad_perm:[1,0,3,2] row_mask:0xf bank_mask:0xf bound_ctrl:1
	s_nop 1
	v_add_f32_dpp v122, v122, v122 quad_perm:[2,3,0,1] row_mask:0xf bank_mask:0xf bound_ctrl:1
	s_nop 1
	v_add_f32_dpp v122, v122, v122 row_half_mirror row_mask:0xf bank_mask:0xf bound_ctrl:1
	s_nop 1
	v_add_f32_dpp v122, v122, v122 row_mirror row_mask:0xf bank_mask:0xf bound_ctrl:1
	v_mov_b32_e32 v123, v122
	s_nop 1
	v_permlane16_swap_b32_e32 v122, v123
	v_add_f32_e32 v122, v122, v123
	v_mov_b32_e32 v123, v122
	s_nop 1
	v_permlane32_swap_b32_e32 v122, v123
	v_add_f32_e32 v122, v122, v123
	v_fmamk_f32 v122, v122, 0x3a800000, v3
	v_rsq_f32_e32 v122, v122
	s_nop 0
	v_mov_b32_e32 v123, v122
	v_pk_mul_f32 v[26:27], v[122:123], v[26:27]
	v_pk_mul_f32 v[26:27], v[10:11], v[26:27]
	v_pk_fma_f32 v[26:27], v[74:75], v[26:27], v[58:59]
	v_pk_mul_f32 v[28:29], v[122:123], v[28:29]
	v_pk_mul_f32 v[28:29], v[12:13], v[28:29]
	v_pk_fma_f32 v[28:29], v[76:77], v[28:29], v[60:61]
	v_cvt_pk_bf16_f32 v124, v26, v27
	v_cvt_pk_bf16_f32 v125, v28, v29
	global_store_dwordx2 v2, v[124:125], s[8:9]
	v_pk_mul_f32 v[30:31], v[122:123], v[30:31]
	v_pk_mul_f32 v[30:31], v[14:15], v[30:31]
	v_pk_fma_f32 v[30:31], v[78:79], v[30:31], v[62:63]
	v_pk_mul_f32 v[32:33], v[122:123], v[32:33]
	v_pk_mul_f32 v[32:33], v[16:17], v[32:33]
	v_pk_fma_f32 v[32:33], v[80:81], v[32:33], v[64:65]
	v_cvt_pk_bf16_f32 v126, v30, v31
	v_cvt_pk_bf16_f32 v127, v32, v33
	global_store_dwordx2 v2, v[126:127], s[8:9] offset:512
	v_pk_mul_f32 v[34:35], v[122:123], v[34:35]
	v_pk_mul_f32 v[34:35], v[18:19], v[34:35]
	v_pk_fma_f32 v[34:35], v[82:83], v[34:35], v[66:67]
	v_pk_mul_f32 v[36:37], v[122:123], v[36:37]
	v_pk_mul_f32 v[36:37], v[20:21], v[36:37]
	v_pk_fma_f32 v[36:37], v[84:85], v[36:37], v[68:69]
	v_cvt_pk_bf16_f32 v124, v34, v35
	v_cvt_pk_bf16_f32 v125, v36, v37
	global_store_dwordx2 v2, v[124:125], s[8:9] offset:1024
	v_pk_mul_f32 v[38:39], v[122:123], v[38:39]
	v_pk_mul_f32 v[38:39], v[22:23], v[38:39]
	v_pk_fma_f32 v[38:39], v[86:87], v[38:39], v[70:71]
	v_pk_mul_f32 v[40:41], v[122:123], v[40:41]
	v_pk_mul_f32 v[40:41], v[24:25], v[40:41]
	v_pk_fma_f32 v[40:41], v[88:89], v[40:41], v[72:73]
	v_cvt_pk_bf16_f32 v126, v38, v39
	v_cvt_pk_bf16_f32 v127, v40, v41
	global_store_dwordx2 v2, v[126:127], s[8:9] offset:1536
	s_add_u32 s8, s8, 0x800
	s_addc_u32 s9, s9, 0
	global_load_dwordx4 v[26:29], v1, s[4:5] nt
	global_load_dwordx4 v[30:33], v1, s[4:5] offset:1024 nt
	global_load_dwordx4 v[34:37], v1, s[4:5] offset:2048 nt
	global_load_dwordx4 v[38:41], v1, s[4:5] offset:3072 nt
	s_add_u32 s4, s4, 0x1000
	s_addc_u32 s5, s5, 0
	s_waitcnt vmcnt(16)
	v_mul_f32_e32 v122, v42, v42
	v_fmac_f32_e32 v122, v43, v43
	v_fmac_f32_e32 v122, v44, v44
	v_fmac_f32_e32 v122, v45, v45
	v_mul_f32_e32 v123, v46, v46
	v_fmac_f32_e32 v123, v47, v47
	v_fmac_f32_e32 v123, v48, v48
	v_fmac_f32_e32 v123, v49, v49
	v_mul_f32_e32 v124, v50, v50
	v_fmac_f32_e32 v124, v51, v51
	v_fmac_f32_e32 v124, v52, v52
	v_fmac_f32_e32 v124, v53, v53
	v_mul_f32_e32 v125, v54, v54
	v_fmac_f32_e32 v125, v55, v55
	v_fmac_f32_e32 v125, v56, v56
	v_fmac_f32_e32 v125, v57, v57
	v_add_f32_e32 v122, v122, v123
	v_add_f32_e32 v124, v124, v125
	v_add_f32_e32 v122, v122, v124
	s_nop 1
	v_add_f32_dpp v122, v122, v122 quad_perm:[1,0,3,2] row_mask:0xf bank_mask:0xf bound_ctrl:1
	s_nop 1
	v_add_f32_dpp v122, v122, v122 quad_perm:[2,3,0,1] row_mask:0xf bank_mask:0xf bound_ctrl:1
	s_nop 1
	v_add_f32_dpp v122, v122, v122 row_half_mirror row_mask:0xf bank_mask:0xf bound_ctrl:1
	s_nop 1
	v_add_f32_dpp v122, v122, v122 row_mirror row_mask:0xf bank_mask:0xf bound_ctrl:1
	v_mov_b32_e32 v123, v122
	s_nop 1
	v_permlane16_swap_b32_e32 v122, v123
	v_add_f32_e32 v122, v122, v123
	v_mov_b32_e32 v123, v122
	s_nop 1
	v_permlane32_swap_b32_e32 v122, v123
	v_add_f32_e32 v122, v122, v123
	v_fmamk_f32 v122, v122, 0x3a800000, v3
	v_rsq_f32_e32 v122, v122
	s_nop 0
	v_mov_b32_e32 v123, v122
	v_pk_mul_f32 v[42:43], v[122:123], v[42:43]
	v_pk_mul_f32 v[42:43], v[10:11], v[42:43]
	v_pk_fma_f32 v[42:43], v[74:75], v[42:43], v[58:59]
	v_pk_mul_f32 v[44:45], v[122:123], v[44:45]
	v_pk_mul_f32 v[44:45], v[12:13], v[44:45]
	v_pk_fma_f32 v[44:45], v[76:77], v[44:45], v[60:61]
	v_cvt_pk_bf16_f32 v124, v42, v43
	v_cvt_pk_bf16_f32 v125, v44, v45
	global_store_dwordx2 v2, v[124:125], s[8:9]
	v_pk_mul_f32 v[46:47], v[122:123], v[46:47]
	v_pk_mul_f32 v[46:47], v[14:15], v[46:47]
	v_pk_fma_f32 v[46:47], v[78:79], v[46:47], v[62:63]
	v_pk_mul_f32 v[48:49], v[122:123], v[48:49]
	v_pk_mul_f32 v[48:49], v[16:17], v[48:49]
	v_pk_fma_f32 v[48:49], v[80:81], v[48:49], v[64:65]
	v_cvt_pk_bf16_f32 v126, v46, v47
	v_cvt_pk_bf16_f32 v127, v48, v49
	global_store_dwordx2 v2, v[126:127], s[8:9] offset:512
	v_pk_mul_f32 v[50:51], v[122:123], v[50:51]
	v_pk_mul_f32 v[50:51], v[18:19], v[50:51]
	v_pk_fma_f32 v[50:51], v[82:83], v[50:51], v[66:67]
	v_pk_mul_f32 v[52:53], v[122:123], v[52:53]
	v_pk_mul_f32 v[52:53], v[20:21], v[52:53]
	v_pk_fma_f32 v[52:53], v[84:85], v[52:53], v[68:69]
	v_cvt_pk_bf16_f32 v124, v50, v51
	v_cvt_pk_bf16_f32 v125, v52, v53
	global_store_dwordx2 v2, v[124:125], s[8:9] offset:1024
	v_pk_mul_f32 v[54:55], v[122:123], v[54:55]
	v_pk_mul_f32 v[54:55], v[22:23], v[54:55]
	v_pk_fma_f32 v[54:55], v[86:87], v[54:55], v[70:71]
	v_pk_mul_f32 v[56:57], v[122:123], v[56:57]
	v_pk_mul_f32 v[56:57], v[24:25], v[56:57]
	v_pk_fma_f32 v[56:57], v[88:89], v[56:57], v[72:73]
	v_cvt_pk_bf16_f32 v126, v54, v55
	v_cvt_pk_bf16_f32 v127, v56, v57
	global_store_dwordx2 v2, v[126:127], s[8:9] offset:1536
	s_add_u32 s8, s8, 0x800
	s_addc_u32 s9, s9, 0
	global_load_dwordx4 v[42:45], v1, s[4:5] nt
	global_load_dwordx4 v[46:49], v1, s[4:5] offset:1024 nt
	global_load_dwordx4 v[50:53], v1, s[4:5] offset:2048 nt
	global_load_dwordx4 v[54:57], v1, s[4:5] offset:3072 nt
	s_add_u32 s4, s4, 0x1000
	s_addc_u32 s5, s5, 0
	s_waitcnt vmcnt(16)
	v_mul_f32_e32 v122, v90, v90
	v_fmac_f32_e32 v122, v91, v91
	v_fmac_f32_e32 v122, v92, v92
	v_fmac_f32_e32 v122, v93, v93
	v_mul_f32_e32 v123, v94, v94
	v_fmac_f32_e32 v123, v95, v95
	v_fmac_f32_e32 v123, v96, v96
	v_fmac_f32_e32 v123, v97, v97
	v_mul_f32_e32 v124, v98, v98
	v_fmac_f32_e32 v124, v99, v99
	v_fmac_f32_e32 v124, v100, v100
	v_fmac_f32_e32 v124, v101, v101
	v_mul_f32_e32 v125, v102, v102
	v_fmac_f32_e32 v125, v103, v103
	v_fmac_f32_e32 v125, v104, v104
	v_fmac_f32_e32 v125, v105, v105
	v_add_f32_e32 v122, v122, v123
	v_add_f32_e32 v124, v124, v125
	v_add_f32_e32 v122, v122, v124
	s_nop 1
	v_add_f32_dpp v122, v122, v122 quad_perm:[1,0,3,2] row_mask:0xf bank_mask:0xf bound_ctrl:1
	s_nop 1
	v_add_f32_dpp v122, v122, v122 quad_perm:[2,3,0,1] row_mask:0xf bank_mask:0xf bound_ctrl:1
	s_nop 1
	v_add_f32_dpp v122, v122, v122 row_half_mirror row_mask:0xf bank_mask:0xf bound_ctrl:1
	s_nop 1
	v_add_f32_dpp v122, v122, v122 row_mirror row_mask:0xf bank_mask:0xf bound_ctrl:1
	v_mov_b32_e32 v123, v122
	s_nop 1
	v_permlane16_swap_b32_e32 v122, v123
	v_add_f32_e32 v122, v122, v123
	v_mov_b32_e32 v123, v122
	s_nop 1
	v_permlane32_swap_b32_e32 v122, v123
	v_add_f32_e32 v122, v122, v123
	v_fmamk_f32 v122, v122, 0x3a800000, v3
	v_rsq_f32_e32 v122, v122
	s_nop 0
	v_mov_b32_e32 v123, v122
	v_pk_mul_f32 v[90:91], v[122:123], v[90:91]
	v_pk_mul_f32 v[90:91], v[10:11], v[90:91]
	v_pk_fma_f32 v[90:91], v[74:75], v[90:91], v[58:59]
	v_pk_mul_f32 v[92:93], v[122:123], v[92:93]
	v_pk_mul_f32 v[92:93], v[12:13], v[92:93]
	v_pk_fma_f32 v[92:93], v[76:77], v[92:93], v[60:61]
	v_cvt_pk_bf16_f32 v124, v90, v91
	v_cvt_pk_bf16_f32 v125, v92, v93
	global_store_dwordx2 v2, v[124:125], s[8:9]
	v_pk_mul_f32 v[94:95], v[122:123], v[94:95]
	v_pk_mul_f32 v[94:95], v[14:15], v[94:95]
	v_pk_fma_f32 v[94:95], v[78:79], v[94:95], v[62:63]
	v_pk_mul_f32 v[96:97], v[122:123], v[96:97]
	v_pk_mul_f32 v[96:97], v[16:17], v[96:97]
	v_pk_fma_f32 v[96:97], v[80:81], v[96:97], v[64:65]
	v_cvt_pk_bf16_f32 v126, v94, v95
	v_cvt_pk_bf16_f32 v127, v96, v97
	global_store_dwordx2 v2, v[126:127], s[8:9] offset:512
	v_pk_mul_f32 v[98:99], v[122:123], v[98:99]
	v_pk_mul_f32 v[98:99], v[18:19], v[98:99]
	v_pk_fma_f32 v[98:99], v[82:83], v[98:99], v[66:67]
	v_pk_mul_f32 v[100:101], v[122:123], v[100:101]
	v_pk_mul_f32 v[100:101], v[20:21], v[100:101]
	v_pk_fma_f32 v[100:101], v[84:85], v[100:101], v[68:69]
	v_cvt_pk_bf16_f32 v124, v98, v99
	v_cvt_pk_bf16_f32 v125, v100, v101
	global_store_dwordx2 v2, v[124:125], s[8:9] offset:1024
	v_pk_mul_f32 v[102:103], v[122:123], v[102:103]
	v_pk_mul_f32 v[102:103], v[22:23], v[102:103]
	v_pk_fma_f32 v[102:103], v[86:87], v[102:103], v[70:71]
	v_pk_mul_f32 v[104:105], v[122:123], v[104:105]
	v_pk_mul_f32 v[104:105], v[24:25], v[104:105]
	v_pk_fma_f32 v[104:105], v[88:89], v[104:105], v[72:73]
	v_cvt_pk_bf16_f32 v126, v102, v103
	v_cvt_pk_bf16_f32 v127, v104, v105
	global_store_dwordx2 v2, v[126:127], s[8:9] offset:1536
	s_add_u32 s8, s8, 0x800
	s_addc_u32 s9, s9, 0
	global_load_dwordx4 v[90:93], v1, s[4:5] nt
	global_load_dwordx4 v[94:97], v1, s[4:5] offset:1024 nt
	global_load_dwordx4 v[98:101], v1, s[4:5] offset:2048 nt
	global_load_dwordx4 v[102:105], v1, s[4:5] offset:3072 nt
	s_add_u32 s4, s4, 0x1000
	s_addc_u32 s5, s5, 0
	s_waitcnt vmcnt(16)
	v_mul_f32_e32 v122, v26, v26
	v_fmac_f32_e32 v122, v27, v27
	v_fmac_f32_e32 v122, v28, v28
	v_fmac_f32_e32 v122, v29, v29
	v_mul_f32_e32 v123, v30, v30
	v_fmac_f32_e32 v123, v31, v31
	v_fmac_f32_e32 v123, v32, v32
	v_fmac_f32_e32 v123, v33, v33
	v_mul_f32_e32 v124, v34, v34
	v_fmac_f32_e32 v124, v35, v35
	v_fmac_f32_e32 v124, v36, v36
	v_fmac_f32_e32 v124, v37, v37
	v_mul_f32_e32 v125, v38, v38
	v_fmac_f32_e32 v125, v39, v39
	v_fmac_f32_e32 v125, v40, v40
	v_fmac_f32_e32 v125, v41, v41
	v_add_f32_e32 v122, v122, v123
	v_add_f32_e32 v124, v124, v125
	v_add_f32_e32 v122, v122, v124
	s_nop 1
	v_add_f32_dpp v122, v122, v122 quad_perm:[1,0,3,2] row_mask:0xf bank_mask:0xf bound_ctrl:1
	s_nop 1
	v_add_f32_dpp v122, v122, v122 quad_perm:[2,3,0,1] row_mask:0xf bank_mask:0xf bound_ctrl:1
	s_nop 1
	v_add_f32_dpp v122, v122, v122 row_half_mirror row_mask:0xf bank_mask:0xf bound_ctrl:1
	s_nop 1
	v_add_f32_dpp v122, v122, v122 row_mirror row_mask:0xf bank_mask:0xf bound_ctrl:1
	v_mov_b32_e32 v123, v122
	s_nop 1
	v_permlane16_swap_b32_e32 v122, v123
	v_add_f32_e32 v122, v122, v123
	v_mov_b32_e32 v123, v122
	s_nop 1
	v_permlane32_swap_b32_e32 v122, v123
	v_add_f32_e32 v122, v122, v123
	v_fmamk_f32 v122, v122, 0x3a800000, v3
	v_rsq_f32_e32 v122, v122
	s_nop 0
	v_mov_b32_e32 v123, v122
	v_pk_mul_f32 v[26:27], v[122:123], v[26:27]
	v_pk_mul_f32 v[26:27], v[10:11], v[26:27]
	v_pk_fma_f32 v[26:27], v[74:75], v[26:27], v[58:59]
	v_pk_mul_f32 v[28:29], v[122:123], v[28:29]
	v_pk_mul_f32 v[28:29], v[12:13], v[28:29]
	v_pk_fma_f32 v[28:29], v[76:77], v[28:29], v[60:61]
	v_cvt_pk_bf16_f32 v124, v26, v27
	v_cvt_pk_bf16_f32 v125, v28, v29
	global_store_dwordx2 v2, v[124:125], s[8:9]
	v_pk_mul_f32 v[30:31], v[122:123], v[30:31]
	v_pk_mul_f32 v[30:31], v[14:15], v[30:31]
	v_pk_fma_f32 v[30:31], v[78:79], v[30:31], v[62:63]
	v_pk_mul_f32 v[32:33], v[122:123], v[32:33]
	v_pk_mul_f32 v[32:33], v[16:17], v[32:33]
	v_pk_fma_f32 v[32:33], v[80:81], v[32:33], v[64:65]
	v_cvt_pk_bf16_f32 v126, v30, v31
	v_cvt_pk_bf16_f32 v127, v32, v33
	global_store_dwordx2 v2, v[126:127], s[8:9] offset:512
	v_pk_mul_f32 v[34:35], v[122:123], v[34:35]
	v_pk_mul_f32 v[34:35], v[18:19], v[34:35]
	v_pk_fma_f32 v[34:35], v[82:83], v[34:35], v[66:67]
	v_pk_mul_f32 v[36:37], v[122:123], v[36:37]
	v_pk_mul_f32 v[36:37], v[20:21], v[36:37]
	v_pk_fma_f32 v[36:37], v[84:85], v[36:37], v[68:69]
	v_cvt_pk_bf16_f32 v124, v34, v35
	v_cvt_pk_bf16_f32 v125, v36, v37
	global_store_dwordx2 v2, v[124:125], s[8:9] offset:1024
	v_pk_mul_f32 v[38:39], v[122:123], v[38:39]
	v_pk_mul_f32 v[38:39], v[22:23], v[38:39]
	v_pk_fma_f32 v[38:39], v[86:87], v[38:39], v[70:71]
	v_pk_mul_f32 v[40:41], v[122:123], v[40:41]
	v_pk_mul_f32 v[40:41], v[24:25], v[40:41]
	v_pk_fma_f32 v[40:41], v[88:89], v[40:41], v[72:73]
	v_cvt_pk_bf16_f32 v126, v38, v39
	v_cvt_pk_bf16_f32 v127, v40, v41
	global_store_dwordx2 v2, v[126:127], s[8:9] offset:1536
	s_add_u32 s8, s8, 0x800
	s_addc_u32 s9, s9, 0
	global_load_dwordx4 v[26:29], v1, s[4:5] nt
	global_load_dwordx4 v[30:33], v1, s[4:5] offset:1024 nt
	global_load_dwordx4 v[34:37], v1, s[4:5] offset:2048 nt
	global_load_dwordx4 v[38:41], v1, s[4:5] offset:3072 nt
	s_add_u32 s4, s4, 0x1000
	s_addc_u32 s5, s5, 0
	s_waitcnt vmcnt(16)
	v_mul_f32_e32 v122, v42, v42
	v_fmac_f32_e32 v122, v43, v43
	v_fmac_f32_e32 v122, v44, v44
	v_fmac_f32_e32 v122, v45, v45
	v_mul_f32_e32 v123, v46, v46
	v_fmac_f32_e32 v123, v47, v47
	v_fmac_f32_e32 v123, v48, v48
	v_fmac_f32_e32 v123, v49, v49
	v_mul_f32_e32 v124, v50, v50
	v_fmac_f32_e32 v124, v51, v51
	v_fmac_f32_e32 v124, v52, v52
	v_fmac_f32_e32 v124, v53, v53
	v_mul_f32_e32 v125, v54, v54
	v_fmac_f32_e32 v125, v55, v55
	v_fmac_f32_e32 v125, v56, v56
	v_fmac_f32_e32 v125, v57, v57
	v_add_f32_e32 v122, v122, v123
	v_add_f32_e32 v124, v124, v125
	v_add_f32_e32 v122, v122, v124
	s_nop 1
	v_add_f32_dpp v122, v122, v122 quad_perm:[1,0,3,2] row_mask:0xf bank_mask:0xf bound_ctrl:1
	s_nop 1
	v_add_f32_dpp v122, v122, v122 quad_perm:[2,3,0,1] row_mask:0xf bank_mask:0xf bound_ctrl:1
	s_nop 1
	v_add_f32_dpp v122, v122, v122 row_half_mirror row_mask:0xf bank_mask:0xf bound_ctrl:1
	s_nop 1
	v_add_f32_dpp v122, v122, v122 row_mirror row_mask:0xf bank_mask:0xf bound_ctrl:1
	v_mov_b32_e32 v123, v122
	s_nop 1
	v_permlane16_swap_b32_e32 v122, v123
	v_add_f32_e32 v122, v122, v123
	v_mov_b32_e32 v123, v122
	s_nop 1
	v_permlane32_swap_b32_e32 v122, v123
	v_add_f32_e32 v122, v122, v123
	v_fmamk_f32 v122, v122, 0x3a800000, v3
	v_rsq_f32_e32 v122, v122
	s_nop 0
	v_mov_b32_e32 v123, v122
	v_pk_mul_f32 v[42:43], v[122:123], v[42:43]
	v_pk_mul_f32 v[42:43], v[10:11], v[42:43]
	v_pk_fma_f32 v[42:43], v[74:75], v[42:43], v[58:59]
	v_pk_mul_f32 v[44:45], v[122:123], v[44:45]
	v_pk_mul_f32 v[44:45], v[12:13], v[44:45]
	v_pk_fma_f32 v[44:45], v[76:77], v[44:45], v[60:61]
	v_cvt_pk_bf16_f32 v124, v42, v43
	v_cvt_pk_bf16_f32 v125, v44, v45
	global_store_dwordx2 v2, v[124:125], s[8:9]
	v_pk_mul_f32 v[46:47], v[122:123], v[46:47]
	v_pk_mul_f32 v[46:47], v[14:15], v[46:47]
	v_pk_fma_f32 v[46:47], v[78:79], v[46:47], v[62:63]
	v_pk_mul_f32 v[48:49], v[122:123], v[48:49]
	v_pk_mul_f32 v[48:49], v[16:17], v[48:49]
	v_pk_fma_f32 v[48:49], v[80:81], v[48:49], v[64:65]
	v_cvt_pk_bf16_f32 v126, v46, v47
	v_cvt_pk_bf16_f32 v127, v48, v49
	global_store_dwordx2 v2, v[126:127], s[8:9] offset:512
	v_pk_mul_f32 v[50:51], v[122:123], v[50:51]
	v_pk_mul_f32 v[50:51], v[18:19], v[50:51]
	v_pk_fma_f32 v[50:51], v[82:83], v[50:51], v[66:67]
	v_pk_mul_f32 v[52:53], v[122:123], v[52:53]
	v_pk_mul_f32 v[52:53], v[20:21], v[52:53]
	v_pk_fma_f32 v[52:53], v[84:85], v[52:53], v[68:69]
	v_cvt_pk_bf16_f32 v124, v50, v51
	v_cvt_pk_bf16_f32 v125, v52, v53
	global_store_dwordx2 v2, v[124:125], s[8:9] offset:1024
	v_pk_mul_f32 v[54:55], v[122:123], v[54:55]
	v_pk_mul_f32 v[54:55], v[22:23], v[54:55]
	v_pk_fma_f32 v[54:55], v[86:87], v[54:55], v[70:71]
	v_pk_mul_f32 v[56:57], v[122:123], v[56:57]
	v_pk_mul_f32 v[56:57], v[24:25], v[56:57]
	v_pk_fma_f32 v[56:57], v[88:89], v[56:57], v[72:73]
	v_cvt_pk_bf16_f32 v126, v54, v55
	v_cvt_pk_bf16_f32 v127, v56, v57
	global_store_dwordx2 v2, v[126:127], s[8:9] offset:1536
	s_add_u32 s8, s8, 0x800
	s_addc_u32 s9, s9, 0
	global_load_dwordx4 v[42:45], v1, s[4:5] nt
	global_load_dwordx4 v[46:49], v1, s[4:5] offset:1024 nt
	global_load_dwordx4 v[50:53], v1, s[4:5] offset:2048 nt
	global_load_dwordx4 v[54:57], v1, s[4:5] offset:3072 nt
	s_add_u32 s4, s4, 0x1000
	s_addc_u32 s5, s5, 0
	s_waitcnt vmcnt(16)
	v_mul_f32_e32 v122, v90, v90
	v_fmac_f32_e32 v122, v91, v91
	v_fmac_f32_e32 v122, v92, v92
	v_fmac_f32_e32 v122, v93, v93
	v_mul_f32_e32 v123, v94, v94
	v_fmac_f32_e32 v123, v95, v95
	v_fmac_f32_e32 v123, v96, v96
	v_fmac_f32_e32 v123, v97, v97
	v_mul_f32_e32 v124, v98, v98
	v_fmac_f32_e32 v124, v99, v99
	v_fmac_f32_e32 v124, v100, v100
	v_fmac_f32_e32 v124, v101, v101
	v_mul_f32_e32 v125, v102, v102
	v_fmac_f32_e32 v125, v103, v103
	v_fmac_f32_e32 v125, v104, v104
	v_fmac_f32_e32 v125, v105, v105
	v_add_f32_e32 v122, v122, v123
	v_add_f32_e32 v124, v124, v125
	v_add_f32_e32 v122, v122, v124
	s_nop 1
	v_add_f32_dpp v122, v122, v122 quad_perm:[1,0,3,2] row_mask:0xf bank_mask:0xf bound_ctrl:1
	s_nop 1
	v_add_f32_dpp v122, v122, v122 quad_perm:[2,3,0,1] row_mask:0xf bank_mask:0xf bound_ctrl:1
	s_nop 1
	v_add_f32_dpp v122, v122, v122 row_half_mirror row_mask:0xf bank_mask:0xf bound_ctrl:1
	s_nop 1
	v_add_f32_dpp v122, v122, v122 row_mirror row_mask:0xf bank_mask:0xf bound_ctrl:1
	v_mov_b32_e32 v123, v122
	s_nop 1
	v_permlane16_swap_b32_e32 v122, v123
	v_add_f32_e32 v122, v122, v123
	v_mov_b32_e32 v123, v122
	s_nop 1
	v_permlane32_swap_b32_e32 v122, v123
	v_add_f32_e32 v122, v122, v123
	v_fmamk_f32 v122, v122, 0x3a800000, v3
	v_rsq_f32_e32 v122, v122
	s_nop 0
	v_mov_b32_e32 v123, v122
	v_pk_mul_f32 v[90:91], v[122:123], v[90:91]
	v_pk_mul_f32 v[90:91], v[10:11], v[90:91]
	v_pk_fma_f32 v[90:91], v[74:75], v[90:91], v[58:59]
	v_pk_mul_f32 v[92:93], v[122:123], v[92:93]
	v_pk_mul_f32 v[92:93], v[12:13], v[92:93]
	v_pk_fma_f32 v[92:93], v[76:77], v[92:93], v[60:61]
	v_cvt_pk_bf16_f32 v124, v90, v91
	v_cvt_pk_bf16_f32 v125, v92, v93
	global_store_dwordx2 v2, v[124:125], s[8:9]
	v_pk_mul_f32 v[94:95], v[122:123], v[94:95]
	v_pk_mul_f32 v[94:95], v[14:15], v[94:95]
	v_pk_fma_f32 v[94:95], v[78:79], v[94:95], v[62:63]
	v_pk_mul_f32 v[96:97], v[122:123], v[96:97]
	v_pk_mul_f32 v[96:97], v[16:17], v[96:97]
	v_pk_fma_f32 v[96:97], v[80:81], v[96:97], v[64:65]
	v_cvt_pk_bf16_f32 v126, v94, v95
	v_cvt_pk_bf16_f32 v127, v96, v97
	global_store_dwordx2 v2, v[126:127], s[8:9] offset:512
	v_pk_mul_f32 v[98:99], v[122:123], v[98:99]
	v_pk_mul_f32 v[98:99], v[18:19], v[98:99]
	v_pk_fma_f32 v[98:99], v[82:83], v[98:99], v[66:67]
	v_pk_mul_f32 v[100:101], v[122:123], v[100:101]
	v_pk_mul_f32 v[100:101], v[20:21], v[100:101]
	v_pk_fma_f32 v[100:101], v[84:85], v[100:101], v[68:69]
	v_cvt_pk_bf16_f32 v124, v98, v99
	v_cvt_pk_bf16_f32 v125, v100, v101
	global_store_dwordx2 v2, v[124:125], s[8:9] offset:1024
	v_pk_mul_f32 v[102:103], v[122:123], v[102:103]
	v_pk_mul_f32 v[102:103], v[22:23], v[102:103]
	v_pk_fma_f32 v[102:103], v[86:87], v[102:103], v[70:71]
	v_pk_mul_f32 v[104:105], v[122:123], v[104:105]
	v_pk_mul_f32 v[104:105], v[24:25], v[104:105]
	v_pk_fma_f32 v[104:105], v[88:89], v[104:105], v[72:73]
	v_cvt_pk_bf16_f32 v126, v102, v103
	v_cvt_pk_bf16_f32 v127, v104, v105
	global_store_dwordx2 v2, v[126:127], s[8:9] offset:1536
	s_add_u32 s8, s8, 0x800
	s_addc_u32 s9, s9, 0
	global_load_dwordx4 v[90:93], v1, s[4:5] nt
	global_load_dwordx4 v[94:97], v1, s[4:5] offset:1024 nt
	global_load_dwordx4 v[98:101], v1, s[4:5] offset:2048 nt
	global_load_dwordx4 v[102:105], v1, s[4:5] offset:3072 nt
	s_add_u32 s4, s4, 0x1000
	s_addc_u32 s5, s5, 0
	s_waitcnt vmcnt(16)
	v_mul_f32_e32 v122, v26, v26
	v_fmac_f32_e32 v122, v27, v27
	v_fmac_f32_e32 v122, v28, v28
	v_fmac_f32_e32 v122, v29, v29
	v_mul_f32_e32 v123, v30, v30
	v_fmac_f32_e32 v123, v31, v31
	v_fmac_f32_e32 v123, v32, v32
	v_fmac_f32_e32 v123, v33, v33
	v_mul_f32_e32 v124, v34, v34
	v_fmac_f32_e32 v124, v35, v35
	v_fmac_f32_e32 v124, v36, v36
	v_fmac_f32_e32 v124, v37, v37
	v_mul_f32_e32 v125, v38, v38
	v_fmac_f32_e32 v125, v39, v39
	v_fmac_f32_e32 v125, v40, v40
	v_fmac_f32_e32 v125, v41, v41
	v_add_f32_e32 v122, v122, v123
	v_add_f32_e32 v124, v124, v125
	v_add_f32_e32 v122, v122, v124
	s_nop 1
	v_add_f32_dpp v122, v122, v122 quad_perm:[1,0,3,2] row_mask:0xf bank_mask:0xf bound_ctrl:1
	s_nop 1
	v_add_f32_dpp v122, v122, v122 quad_perm:[2,3,0,1] row_mask:0xf bank_mask:0xf bound_ctrl:1
	s_nop 1
	v_add_f32_dpp v122, v122, v122 row_half_mirror row_mask:0xf bank_mask:0xf bound_ctrl:1
	s_nop 1
	v_add_f32_dpp v122, v122, v122 row_mirror row_mask:0xf bank_mask:0xf bound_ctrl:1
	v_mov_b32_e32 v123, v122
	s_nop 1
	v_permlane16_swap_b32_e32 v122, v123
	v_add_f32_e32 v122, v122, v123
	v_mov_b32_e32 v123, v122
	s_nop 1
	v_permlane32_swap_b32_e32 v122, v123
	v_add_f32_e32 v122, v122, v123
	v_fmamk_f32 v122, v122, 0x3a800000, v3
	v_rsq_f32_e32 v122, v122
	s_nop 0
	v_mov_b32_e32 v123, v122
	v_pk_mul_f32 v[26:27], v[122:123], v[26:27]
	v_pk_mul_f32 v[26:27], v[10:11], v[26:27]
	v_pk_fma_f32 v[26:27], v[74:75], v[26:27], v[58:59]
	v_pk_mul_f32 v[28:29], v[122:123], v[28:29]
	v_pk_mul_f32 v[28:29], v[12:13], v[28:29]
	v_pk_fma_f32 v[28:29], v[76:77], v[28:29], v[60:61]
	v_cvt_pk_bf16_f32 v124, v26, v27
	v_cvt_pk_bf16_f32 v125, v28, v29
	global_store_dwordx2 v2, v[124:125], s[8:9]
	v_pk_mul_f32 v[30:31], v[122:123], v[30:31]
	v_pk_mul_f32 v[30:31], v[14:15], v[30:31]
	v_pk_fma_f32 v[30:31], v[78:79], v[30:31], v[62:63]
	v_pk_mul_f32 v[32:33], v[122:123], v[32:33]
	v_pk_mul_f32 v[32:33], v[16:17], v[32:33]
	v_pk_fma_f32 v[32:33], v[80:81], v[32:33], v[64:65]
	v_cvt_pk_bf16_f32 v126, v30, v31
	v_cvt_pk_bf16_f32 v127, v32, v33
	global_store_dwordx2 v2, v[126:127], s[8:9] offset:512
	v_pk_mul_f32 v[34:35], v[122:123], v[34:35]
	v_pk_mul_f32 v[34:35], v[18:19], v[34:35]
	v_pk_fma_f32 v[34:35], v[82:83], v[34:35], v[66:67]
	v_pk_mul_f32 v[36:37], v[122:123], v[36:37]
	v_pk_mul_f32 v[36:37], v[20:21], v[36:37]
	v_pk_fma_f32 v[36:37], v[84:85], v[36:37], v[68:69]
	v_cvt_pk_bf16_f32 v124, v34, v35
	v_cvt_pk_bf16_f32 v125, v36, v37
	global_store_dwordx2 v2, v[124:125], s[8:9] offset:1024
	v_pk_mul_f32 v[38:39], v[122:123], v[38:39]
	v_pk_mul_f32 v[38:39], v[22:23], v[38:39]
	v_pk_fma_f32 v[38:39], v[86:87], v[38:39], v[70:71]
	v_pk_mul_f32 v[40:41], v[122:123], v[40:41]
	v_pk_mul_f32 v[40:41], v[24:25], v[40:41]
	v_pk_fma_f32 v[40:41], v[88:89], v[40:41], v[72:73]
	v_cvt_pk_bf16_f32 v126, v38, v39
	v_cvt_pk_bf16_f32 v127, v40, v41
	global_store_dwordx2 v2, v[126:127], s[8:9] offset:1536
	s_add_u32 s8, s8, 0x800
	s_addc_u32 s9, s9, 0
	global_load_dwordx4 v[26:29], v1, s[4:5] nt
	global_load_dwordx4 v[30:33], v1, s[4:5] offset:1024 nt
	global_load_dwordx4 v[34:37], v1, s[4:5] offset:2048 nt
	global_load_dwordx4 v[38:41], v1, s[4:5] offset:3072 nt
	s_add_u32 s4, s4, 0x1000
	s_addc_u32 s5, s5, 0
	s_waitcnt vmcnt(16)
	v_mul_f32_e32 v122, v42, v42
	v_fmac_f32_e32 v122, v43, v43
	v_fmac_f32_e32 v122, v44, v44
	v_fmac_f32_e32 v122, v45, v45
	v_mul_f32_e32 v123, v46, v46
	v_fmac_f32_e32 v123, v47, v47
	v_fmac_f32_e32 v123, v48, v48
	v_fmac_f32_e32 v123, v49, v49
	v_mul_f32_e32 v124, v50, v50
	v_fmac_f32_e32 v124, v51, v51
	v_fmac_f32_e32 v124, v52, v52
	v_fmac_f32_e32 v124, v53, v53
	v_mul_f32_e32 v125, v54, v54
	v_fmac_f32_e32 v125, v55, v55
	v_fmac_f32_e32 v125, v56, v56
	v_fmac_f32_e32 v125, v57, v57
	v_add_f32_e32 v122, v122, v123
	v_add_f32_e32 v124, v124, v125
	v_add_f32_e32 v122, v122, v124
	s_nop 1
	v_add_f32_dpp v122, v122, v122 quad_perm:[1,0,3,2] row_mask:0xf bank_mask:0xf bound_ctrl:1
	s_nop 1
	v_add_f32_dpp v122, v122, v122 quad_perm:[2,3,0,1] row_mask:0xf bank_mask:0xf bound_ctrl:1
	s_nop 1
	v_add_f32_dpp v122, v122, v122 row_half_mirror row_mask:0xf bank_mask:0xf bound_ctrl:1
	s_nop 1
	v_add_f32_dpp v122, v122, v122 row_mirror row_mask:0xf bank_mask:0xf bound_ctrl:1
	v_mov_b32_e32 v123, v122
	s_nop 1
	v_permlane16_swap_b32_e32 v122, v123
	v_add_f32_e32 v122, v122, v123
	v_mov_b32_e32 v123, v122
	s_nop 1
	v_permlane32_swap_b32_e32 v122, v123
	v_add_f32_e32 v122, v122, v123
	v_fmamk_f32 v122, v122, 0x3a800000, v3
	v_rsq_f32_e32 v122, v122
	s_nop 0
	v_mov_b32_e32 v123, v122
	v_pk_mul_f32 v[42:43], v[122:123], v[42:43]
	v_pk_mul_f32 v[42:43], v[10:11], v[42:43]
	v_pk_fma_f32 v[42:43], v[74:75], v[42:43], v[58:59]
	v_pk_mul_f32 v[44:45], v[122:123], v[44:45]
	v_pk_mul_f32 v[44:45], v[12:13], v[44:45]
	v_pk_fma_f32 v[44:45], v[76:77], v[44:45], v[60:61]
	v_cvt_pk_bf16_f32 v124, v42, v43
	v_cvt_pk_bf16_f32 v125, v44, v45
	global_store_dwordx2 v2, v[124:125], s[8:9]
	v_pk_mul_f32 v[46:47], v[122:123], v[46:47]
	v_pk_mul_f32 v[46:47], v[14:15], v[46:47]
	v_pk_fma_f32 v[46:47], v[78:79], v[46:47], v[62:63]
	v_pk_mul_f32 v[48:49], v[122:123], v[48:49]
	v_pk_mul_f32 v[48:49], v[16:17], v[48:49]
	v_pk_fma_f32 v[48:49], v[80:81], v[48:49], v[64:65]
	v_cvt_pk_bf16_f32 v126, v46, v47
	v_cvt_pk_bf16_f32 v127, v48, v49
	global_store_dwordx2 v2, v[126:127], s[8:9] offset:512
	v_pk_mul_f32 v[50:51], v[122:123], v[50:51]
	v_pk_mul_f32 v[50:51], v[18:19], v[50:51]
	v_pk_fma_f32 v[50:51], v[82:83], v[50:51], v[66:67]
	v_pk_mul_f32 v[52:53], v[122:123], v[52:53]
	v_pk_mul_f32 v[52:53], v[20:21], v[52:53]
	v_pk_fma_f32 v[52:53], v[84:85], v[52:53], v[68:69]
	v_cvt_pk_bf16_f32 v124, v50, v51
	v_cvt_pk_bf16_f32 v125, v52, v53
	global_store_dwordx2 v2, v[124:125], s[8:9] offset:1024
	v_pk_mul_f32 v[54:55], v[122:123], v[54:55]
	v_pk_mul_f32 v[54:55], v[22:23], v[54:55]
	v_pk_fma_f32 v[54:55], v[86:87], v[54:55], v[70:71]
	v_pk_mul_f32 v[56:57], v[122:123], v[56:57]
	v_pk_mul_f32 v[56:57], v[24:25], v[56:57]
	v_pk_fma_f32 v[56:57], v[88:89], v[56:57], v[72:73]
	v_cvt_pk_bf16_f32 v126, v54, v55
	v_cvt_pk_bf16_f32 v127, v56, v57
	global_store_dwordx2 v2, v[126:127], s[8:9] offset:1536
	s_add_u32 s8, s8, 0x800
	s_addc_u32 s9, s9, 0
	global_load_dwordx4 v[42:45], v1, s[4:5] nt
	global_load_dwordx4 v[46:49], v1, s[4:5] offset:1024 nt
	global_load_dwordx4 v[50:53], v1, s[4:5] offset:2048 nt
	global_load_dwordx4 v[54:57], v1, s[4:5] offset:3072 nt
	s_add_u32 s4, s4, 0x1000
	s_addc_u32 s5, s5, 0
	s_waitcnt vmcnt(16)
	v_mul_f32_e32 v122, v90, v90
	v_fmac_f32_e32 v122, v91, v91
	v_fmac_f32_e32 v122, v92, v92
	v_fmac_f32_e32 v122, v93, v93
	v_mul_f32_e32 v123, v94, v94
	v_fmac_f32_e32 v123, v95, v95
	v_fmac_f32_e32 v123, v96, v96
	v_fmac_f32_e32 v123, v97, v97
	v_mul_f32_e32 v124, v98, v98
	v_fmac_f32_e32 v124, v99, v99
	v_fmac_f32_e32 v124, v100, v100
	v_fmac_f32_e32 v124, v101, v101
	v_mul_f32_e32 v125, v102, v102
	v_fmac_f32_e32 v125, v103, v103
	v_fmac_f32_e32 v125, v104, v104
	v_fmac_f32_e32 v125, v105, v105
	v_add_f32_e32 v122, v122, v123
	v_add_f32_e32 v124, v124, v125
	v_add_f32_e32 v122, v122, v124
	s_nop 1
	v_add_f32_dpp v122, v122, v122 quad_perm:[1,0,3,2] row_mask:0xf bank_mask:0xf bound_ctrl:1
	s_nop 1
	v_add_f32_dpp v122, v122, v122 quad_perm:[2,3,0,1] row_mask:0xf bank_mask:0xf bound_ctrl:1
	s_nop 1
	v_add_f32_dpp v122, v122, v122 row_half_mirror row_mask:0xf bank_mask:0xf bound_ctrl:1
	s_nop 1
	v_add_f32_dpp v122, v122, v122 row_mirror row_mask:0xf bank_mask:0xf bound_ctrl:1
	v_mov_b32_e32 v123, v122
	s_nop 1
	v_permlane16_swap_b32_e32 v122, v123
	v_add_f32_e32 v122, v122, v123
	v_mov_b32_e32 v123, v122
	s_nop 1
	v_permlane32_swap_b32_e32 v122, v123
	v_add_f32_e32 v122, v122, v123
	v_fmamk_f32 v122, v122, 0x3a800000, v3
	v_rsq_f32_e32 v122, v122
	s_nop 0
	v_mov_b32_e32 v123, v122
	v_pk_mul_f32 v[90:91], v[122:123], v[90:91]
	v_pk_mul_f32 v[90:91], v[10:11], v[90:91]
	v_pk_fma_f32 v[90:91], v[74:75], v[90:91], v[58:59]
	v_pk_mul_f32 v[92:93], v[122:123], v[92:93]
	v_pk_mul_f32 v[92:93], v[12:13], v[92:93]
	v_pk_fma_f32 v[92:93], v[76:77], v[92:93], v[60:61]
	v_cvt_pk_bf16_f32 v124, v90, v91
	v_cvt_pk_bf16_f32 v125, v92, v93
	global_store_dwordx2 v2, v[124:125], s[8:9]
	v_pk_mul_f32 v[94:95], v[122:123], v[94:95]
	v_pk_mul_f32 v[94:95], v[14:15], v[94:95]
	v_pk_fma_f32 v[94:95], v[78:79], v[94:95], v[62:63]
	v_pk_mul_f32 v[96:97], v[122:123], v[96:97]
	v_pk_mul_f32 v[96:97], v[16:17], v[96:97]
	v_pk_fma_f32 v[96:97], v[80:81], v[96:97], v[64:65]
	v_cvt_pk_bf16_f32 v126, v94, v95
	v_cvt_pk_bf16_f32 v127, v96, v97
	global_store_dwordx2 v2, v[126:127], s[8:9] offset:512
	v_pk_mul_f32 v[98:99], v[122:123], v[98:99]
	v_pk_mul_f32 v[98:99], v[18:19], v[98:99]
	v_pk_fma_f32 v[98:99], v[82:83], v[98:99], v[66:67]
	v_pk_mul_f32 v[100:101], v[122:123], v[100:101]
	v_pk_mul_f32 v[100:101], v[20:21], v[100:101]
	v_pk_fma_f32 v[100:101], v[84:85], v[100:101], v[68:69]
	v_cvt_pk_bf16_f32 v124, v98, v99
	v_cvt_pk_bf16_f32 v125, v100, v101
	global_store_dwordx2 v2, v[124:125], s[8:9] offset:1024
	v_pk_mul_f32 v[102:103], v[122:123], v[102:103]
	v_pk_mul_f32 v[102:103], v[22:23], v[102:103]
	v_pk_fma_f32 v[102:103], v[86:87], v[102:103], v[70:71]
	v_pk_mul_f32 v[104:105], v[122:123], v[104:105]
	v_pk_mul_f32 v[104:105], v[24:25], v[104:105]
	v_pk_fma_f32 v[104:105], v[88:89], v[104:105], v[72:73]
	v_cvt_pk_bf16_f32 v126, v102, v103
	v_cvt_pk_bf16_f32 v127, v104, v105
	global_store_dwordx2 v2, v[126:127], s[8:9] offset:1536
	s_add_u32 s8, s8, 0x800
	s_addc_u32 s9, s9, 0
	global_load_dwordx4 v[90:93], v1, s[4:5] nt
	global_load_dwordx4 v[94:97], v1, s[4:5] offset:1024 nt
	global_load_dwordx4 v[98:101], v1, s[4:5] offset:2048 nt
	global_load_dwordx4 v[102:105], v1, s[4:5] offset:3072 nt
	s_add_u32 s4, s4, 0x1000
	s_addc_u32 s5, s5, 0
	s_waitcnt vmcnt(16)
	v_mul_f32_e32 v122, v26, v26
	v_fmac_f32_e32 v122, v27, v27
	v_fmac_f32_e32 v122, v28, v28
	v_fmac_f32_e32 v122, v29, v29
	v_mul_f32_e32 v123, v30, v30
	v_fmac_f32_e32 v123, v31, v31
	v_fmac_f32_e32 v123, v32, v32
	v_fmac_f32_e32 v123, v33, v33
	v_mul_f32_e32 v124, v34, v34
	v_fmac_f32_e32 v124, v35, v35
	v_fmac_f32_e32 v124, v36, v36
	v_fmac_f32_e32 v124, v37, v37
	v_mul_f32_e32 v125, v38, v38
	v_fmac_f32_e32 v125, v39, v39
	v_fmac_f32_e32 v125, v40, v40
	v_fmac_f32_e32 v125, v41, v41
	v_add_f32_e32 v122, v122, v123
	v_add_f32_e32 v124, v124, v125
	v_add_f32_e32 v122, v122, v124
	s_nop 1
	v_add_f32_dpp v122, v122, v122 quad_perm:[1,0,3,2] row_mask:0xf bank_mask:0xf bound_ctrl:1
	s_nop 1
	v_add_f32_dpp v122, v122, v122 quad_perm:[2,3,0,1] row_mask:0xf bank_mask:0xf bound_ctrl:1
	s_nop 1
	v_add_f32_dpp v122, v122, v122 row_half_mirror row_mask:0xf bank_mask:0xf bound_ctrl:1
	s_nop 1
	v_add_f32_dpp v122, v122, v122 row_mirror row_mask:0xf bank_mask:0xf bound_ctrl:1
	v_mov_b32_e32 v123, v122
	s_nop 1
	v_permlane16_swap_b32_e32 v122, v123
	v_add_f32_e32 v122, v122, v123
	v_mov_b32_e32 v123, v122
	s_nop 1
	v_permlane32_swap_b32_e32 v122, v123
	v_add_f32_e32 v122, v122, v123
	v_fmamk_f32 v122, v122, 0x3a800000, v3
	v_rsq_f32_e32 v122, v122
	s_nop 0
	v_mov_b32_e32 v123, v122
	v_pk_mul_f32 v[26:27], v[122:123], v[26:27]
	v_pk_mul_f32 v[26:27], v[10:11], v[26:27]
	v_pk_fma_f32 v[26:27], v[74:75], v[26:27], v[58:59]
	v_pk_mul_f32 v[28:29], v[122:123], v[28:29]
	v_pk_mul_f32 v[28:29], v[12:13], v[28:29]
	v_pk_fma_f32 v[28:29], v[76:77], v[28:29], v[60:61]
	v_cvt_pk_bf16_f32 v124, v26, v27
	v_cvt_pk_bf16_f32 v125, v28, v29
	global_store_dwordx2 v2, v[124:125], s[8:9]
	v_pk_mul_f32 v[30:31], v[122:123], v[30:31]
	v_pk_mul_f32 v[30:31], v[14:15], v[30:31]
	v_pk_fma_f32 v[30:31], v[78:79], v[30:31], v[62:63]
	v_pk_mul_f32 v[32:33], v[122:123], v[32:33]
	v_pk_mul_f32 v[32:33], v[16:17], v[32:33]
	v_pk_fma_f32 v[32:33], v[80:81], v[32:33], v[64:65]
	v_cvt_pk_bf16_f32 v126, v30, v31
	v_cvt_pk_bf16_f32 v127, v32, v33
	global_store_dwordx2 v2, v[126:127], s[8:9] offset:512
	v_pk_mul_f32 v[34:35], v[122:123], v[34:35]
	v_pk_mul_f32 v[34:35], v[18:19], v[34:35]
	v_pk_fma_f32 v[34:35], v[82:83], v[34:35], v[66:67]
	v_pk_mul_f32 v[36:37], v[122:123], v[36:37]
	v_pk_mul_f32 v[36:37], v[20:21], v[36:37]
	v_pk_fma_f32 v[36:37], v[84:85], v[36:37], v[68:69]
	v_cvt_pk_bf16_f32 v124, v34, v35
	v_cvt_pk_bf16_f32 v125, v36, v37
	global_store_dwordx2 v2, v[124:125], s[8:9] offset:1024
	v_pk_mul_f32 v[38:39], v[122:123], v[38:39]
	v_pk_mul_f32 v[38:39], v[22:23], v[38:39]
	v_pk_fma_f32 v[38:39], v[86:87], v[38:39], v[70:71]
	v_pk_mul_f32 v[40:41], v[122:123], v[40:41]
	v_pk_mul_f32 v[40:41], v[24:25], v[40:41]
	v_pk_fma_f32 v[40:41], v[88:89], v[40:41], v[72:73]
	v_cvt_pk_bf16_f32 v126, v38, v39
	v_cvt_pk_bf16_f32 v127, v40, v41
	global_store_dwordx2 v2, v[126:127], s[8:9] offset:1536
	s_add_u32 s8, s8, 0x800
	s_addc_u32 s9, s9, 0
	global_load_dwordx4 v[26:29], v1, s[4:5] nt
	global_load_dwordx4 v[30:33], v1, s[4:5] offset:1024 nt
	global_load_dwordx4 v[34:37], v1, s[4:5] offset:2048 nt
	global_load_dwordx4 v[38:41], v1, s[4:5] offset:3072 nt
	s_add_u32 s4, s4, 0x1000
	s_addc_u32 s5, s5, 0
	s_waitcnt vmcnt(16)
	v_mul_f32_e32 v122, v42, v42
	v_fmac_f32_e32 v122, v43, v43
	v_fmac_f32_e32 v122, v44, v44
	v_fmac_f32_e32 v122, v45, v45
	v_mul_f32_e32 v123, v46, v46
	v_fmac_f32_e32 v123, v47, v47
	v_fmac_f32_e32 v123, v48, v48
	v_fmac_f32_e32 v123, v49, v49
	v_mul_f32_e32 v124, v50, v50
	v_fmac_f32_e32 v124, v51, v51
	v_fmac_f32_e32 v124, v52, v52
	v_fmac_f32_e32 v124, v53, v53
	v_mul_f32_e32 v125, v54, v54
	v_fmac_f32_e32 v125, v55, v55
	v_fmac_f32_e32 v125, v56, v56
	v_fmac_f32_e32 v125, v57, v57
	v_add_f32_e32 v122, v122, v123
	v_add_f32_e32 v124, v124, v125
	v_add_f32_e32 v122, v122, v124
	s_nop 1
	v_add_f32_dpp v122, v122, v122 quad_perm:[1,0,3,2] row_mask:0xf bank_mask:0xf bound_ctrl:1
	s_nop 1
	v_add_f32_dpp v122, v122, v122 quad_perm:[2,3,0,1] row_mask:0xf bank_mask:0xf bound_ctrl:1
	s_nop 1
	v_add_f32_dpp v122, v122, v122 row_half_mirror row_mask:0xf bank_mask:0xf bound_ctrl:1
	s_nop 1
	v_add_f32_dpp v122, v122, v122 row_mirror row_mask:0xf bank_mask:0xf bound_ctrl:1
	v_mov_b32_e32 v123, v122
	s_nop 1
	v_permlane16_swap_b32_e32 v122, v123
	v_add_f32_e32 v122, v122, v123
	v_mov_b32_e32 v123, v122
	s_nop 1
	v_permlane32_swap_b32_e32 v122, v123
	v_add_f32_e32 v122, v122, v123
	v_fmamk_f32 v122, v122, 0x3a800000, v3
	v_rsq_f32_e32 v122, v122
	s_nop 0
	v_mov_b32_e32 v123, v122
	v_pk_mul_f32 v[42:43], v[122:123], v[42:43]
	v_pk_mul_f32 v[42:43], v[10:11], v[42:43]
	v_pk_fma_f32 v[42:43], v[74:75], v[42:43], v[58:59]
	v_pk_mul_f32 v[44:45], v[122:123], v[44:45]
	v_pk_mul_f32 v[44:45], v[12:13], v[44:45]
	v_pk_fma_f32 v[44:45], v[76:77], v[44:45], v[60:61]
	v_cvt_pk_bf16_f32 v124, v42, v43
	v_cvt_pk_bf16_f32 v125, v44, v45
	global_store_dwordx2 v2, v[124:125], s[8:9]
	v_pk_mul_f32 v[46:47], v[122:123], v[46:47]
	v_pk_mul_f32 v[46:47], v[14:15], v[46:47]
	v_pk_fma_f32 v[46:47], v[78:79], v[46:47], v[62:63]
	v_pk_mul_f32 v[48:49], v[122:123], v[48:49]
	v_pk_mul_f32 v[48:49], v[16:17], v[48:49]
	v_pk_fma_f32 v[48:49], v[80:81], v[48:49], v[64:65]
	v_cvt_pk_bf16_f32 v126, v46, v47
	v_cvt_pk_bf16_f32 v127, v48, v49
	global_store_dwordx2 v2, v[126:127], s[8:9] offset:512
	v_pk_mul_f32 v[50:51], v[122:123], v[50:51]
	v_pk_mul_f32 v[50:51], v[18:19], v[50:51]
	v_pk_fma_f32 v[50:51], v[82:83], v[50:51], v[66:67]
	v_pk_mul_f32 v[52:53], v[122:123], v[52:53]
	v_pk_mul_f32 v[52:53], v[20:21], v[52:53]
	v_pk_fma_f32 v[52:53], v[84:85], v[52:53], v[68:69]
	v_cvt_pk_bf16_f32 v124, v50, v51
	v_cvt_pk_bf16_f32 v125, v52, v53
	global_store_dwordx2 v2, v[124:125], s[8:9] offset:1024
	v_pk_mul_f32 v[54:55], v[122:123], v[54:55]
	v_pk_mul_f32 v[54:55], v[22:23], v[54:55]
	v_pk_fma_f32 v[54:55], v[86:87], v[54:55], v[70:71]
	v_pk_mul_f32 v[56:57], v[122:123], v[56:57]
	v_pk_mul_f32 v[56:57], v[24:25], v[56:57]
	v_pk_fma_f32 v[56:57], v[88:89], v[56:57], v[72:73]
	v_cvt_pk_bf16_f32 v126, v54, v55
	v_cvt_pk_bf16_f32 v127, v56, v57
	global_store_dwordx2 v2, v[126:127], s[8:9] offset:1536
	s_add_u32 s8, s8, 0x800
	s_addc_u32 s9, s9, 0
	s_waitcnt vmcnt(12)
	v_mul_f32_e32 v122, v90, v90
	v_fmac_f32_e32 v122, v91, v91
	v_fmac_f32_e32 v122, v92, v92
	v_fmac_f32_e32 v122, v93, v93
	v_mul_f32_e32 v123, v94, v94
	v_fmac_f32_e32 v123, v95, v95
	v_fmac_f32_e32 v123, v96, v96
	v_fmac_f32_e32 v123, v97, v97
	v_mul_f32_e32 v124, v98, v98
	v_fmac_f32_e32 v124, v99, v99
	v_fmac_f32_e32 v124, v100, v100
	v_fmac_f32_e32 v124, v101, v101
	v_mul_f32_e32 v125, v102, v102
	v_fmac_f32_e32 v125, v103, v103
	v_fmac_f32_e32 v125, v104, v104
	v_fmac_f32_e32 v125, v105, v105
	v_add_f32_e32 v122, v122, v123
	v_add_f32_e32 v124, v124, v125
	v_add_f32_e32 v122, v122, v124
	s_nop 1
	v_add_f32_dpp v122, v122, v122 quad_perm:[1,0,3,2] row_mask:0xf bank_mask:0xf bound_ctrl:1
	s_nop 1
	v_add_f32_dpp v122, v122, v122 quad_perm:[2,3,0,1] row_mask:0xf bank_mask:0xf bound_ctrl:1
	s_nop 1
	v_add_f32_dpp v122, v122, v122 row_half_mirror row_mask:0xf bank_mask:0xf bound_ctrl:1
	s_nop 1
	v_add_f32_dpp v122, v122, v122 row_mirror row_mask:0xf bank_mask:0xf bound_ctrl:1
	v_mov_b32_e32 v123, v122
	s_nop 1
	v_permlane16_swap_b32_e32 v122, v123
	v_add_f32_e32 v122, v122, v123
	v_mov_b32_e32 v123, v122
	s_nop 1
	v_permlane32_swap_b32_e32 v122, v123
	v_add_f32_e32 v122, v122, v123
	v_fmamk_f32 v122, v122, 0x3a800000, v3
	v_rsq_f32_e32 v122, v122
	s_nop 0
	v_mov_b32_e32 v123, v122
	v_pk_mul_f32 v[90:91], v[122:123], v[90:91]
	v_pk_mul_f32 v[90:91], v[10:11], v[90:91]
	v_pk_fma_f32 v[90:91], v[74:75], v[90:91], v[58:59]
	v_pk_mul_f32 v[92:93], v[122:123], v[92:93]
	v_pk_mul_f32 v[92:93], v[12:13], v[92:93]
	v_pk_fma_f32 v[92:93], v[76:77], v[92:93], v[60:61]
	v_cvt_pk_bf16_f32 v124, v90, v91
	v_cvt_pk_bf16_f32 v125, v92, v93
	global_store_dwordx2 v2, v[124:125], s[8:9]
	v_pk_mul_f32 v[94:95], v[122:123], v[94:95]
	v_pk_mul_f32 v[94:95], v[14:15], v[94:95]
	v_pk_fma_f32 v[94:95], v[78:79], v[94:95], v[62:63]
	v_pk_mul_f32 v[96:97], v[122:123], v[96:97]
	v_pk_mul_f32 v[96:97], v[16:17], v[96:97]
	v_pk_fma_f32 v[96:97], v[80:81], v[96:97], v[64:65]
	v_cvt_pk_bf16_f32 v126, v94, v95
	v_cvt_pk_bf16_f32 v127, v96, v97
	global_store_dwordx2 v2, v[126:127], s[8:9] offset:512
	v_pk_mul_f32 v[98:99], v[122:123], v[98:99]
	v_pk_mul_f32 v[98:99], v[18:19], v[98:99]
	v_pk_fma_f32 v[98:99], v[82:83], v[98:99], v[66:67]
	v_pk_mul_f32 v[100:101], v[122:123], v[100:101]
	v_pk_mul_f32 v[100:101], v[20:21], v[100:101]
	v_pk_fma_f32 v[100:101], v[84:85], v[100:101], v[68:69]
	v_cvt_pk_bf16_f32 v124, v98, v99
	v_cvt_pk_bf16_f32 v125, v100, v101
	global_store_dwordx2 v2, v[124:125], s[8:9] offset:1024
	v_pk_mul_f32 v[102:103], v[122:123], v[102:103]
	v_pk_mul_f32 v[102:103], v[22:23], v[102:103]
	v_pk_fma_f32 v[102:103], v[86:87], v[102:103], v[70:71]
	v_pk_mul_f32 v[104:105], v[122:123], v[104:105]
	v_pk_mul_f32 v[104:105], v[24:25], v[104:105]
	v_pk_fma_f32 v[104:105], v[88:89], v[104:105], v[72:73]
	v_cvt_pk_bf16_f32 v126, v102, v103
	v_cvt_pk_bf16_f32 v127, v104, v105
	global_store_dwordx2 v2, v[126:127], s[8:9] offset:1536
	s_add_u32 s8, s8, 0x800
	s_addc_u32 s9, s9, 0
	s_waitcnt vmcnt(8)
	v_mul_f32_e32 v122, v26, v26
	v_fmac_f32_e32 v122, v27, v27
	v_fmac_f32_e32 v122, v28, v28
	v_fmac_f32_e32 v122, v29, v29
	v_mul_f32_e32 v123, v30, v30
	v_fmac_f32_e32 v123, v31, v31
	v_fmac_f32_e32 v123, v32, v32
	v_fmac_f32_e32 v123, v33, v33
	v_mul_f32_e32 v124, v34, v34
	v_fmac_f32_e32 v124, v35, v35
	v_fmac_f32_e32 v124, v36, v36
	v_fmac_f32_e32 v124, v37, v37
	v_mul_f32_e32 v125, v38, v38
	v_fmac_f32_e32 v125, v39, v39
	v_fmac_f32_e32 v125, v40, v40
	v_fmac_f32_e32 v125, v41, v41
	v_add_f32_e32 v122, v122, v123
	v_add_f32_e32 v124, v124, v125
	v_add_f32_e32 v122, v122, v124
	s_nop 1
	v_add_f32_dpp v122, v122, v122 quad_perm:[1,0,3,2] row_mask:0xf bank_mask:0xf bound_ctrl:1
	s_nop 1
	v_add_f32_dpp v122, v122, v122 quad_perm:[2,3,0,1] row_mask:0xf bank_mask:0xf bound_ctrl:1
	s_nop 1
	v_add_f32_dpp v122, v122, v122 row_half_mirror row_mask:0xf bank_mask:0xf bound_ctrl:1
	s_nop 1
	v_add_f32_dpp v122, v122, v122 row_mirror row_mask:0xf bank_mask:0xf bound_ctrl:1
	v_mov_b32_e32 v123, v122
	s_nop 1
	v_permlane16_swap_b32_e32 v122, v123
	v_add_f32_e32 v122, v122, v123
	v_mov_b32_e32 v123, v122
	s_nop 1
	v_permlane32_swap_b32_e32 v122, v123
	v_add_f32_e32 v122, v122, v123
	v_fmamk_f32 v122, v122, 0x3a800000, v3
	v_rsq_f32_e32 v122, v122
	s_nop 0
	v_mov_b32_e32 v123, v122
	v_pk_mul_f32 v[26:27], v[122:123], v[26:27]
	v_pk_mul_f32 v[26:27], v[10:11], v[26:27]
	v_pk_fma_f32 v[26:27], v[74:75], v[26:27], v[58:59]
	v_pk_mul_f32 v[28:29], v[122:123], v[28:29]
	v_pk_mul_f32 v[28:29], v[12:13], v[28:29]
	v_pk_fma_f32 v[28:29], v[76:77], v[28:29], v[60:61]
	v_cvt_pk_bf16_f32 v124, v26, v27
	v_cvt_pk_bf16_f32 v125, v28, v29
	global_store_dwordx2 v2, v[124:125], s[8:9]
	v_pk_mul_f32 v[30:31], v[122:123], v[30:31]
	v_pk_mul_f32 v[30:31], v[14:15], v[30:31]
	v_pk_fma_f32 v[30:31], v[78:79], v[30:31], v[62:63]
	v_pk_mul_f32 v[32:33], v[122:123], v[32:33]
	v_pk_mul_f32 v[32:33], v[16:17], v[32:33]
	v_pk_fma_f32 v[32:33], v[80:81], v[32:33], v[64:65]
	v_cvt_pk_bf16_f32 v126, v30, v31
	v_cvt_pk_bf16_f32 v127, v32, v33
	global_store_dwordx2 v2, v[126:127], s[8:9] offset:512
	v_pk_mul_f32 v[34:35], v[122:123], v[34:35]
	v_pk_mul_f32 v[34:35], v[18:19], v[34:35]
	v_pk_fma_f32 v[34:35], v[82:83], v[34:35], v[66:67]
	v_pk_mul_f32 v[36:37], v[122:123], v[36:37]
	v_pk_mul_f32 v[36:37], v[20:21], v[36:37]
	v_pk_fma_f32 v[36:37], v[84:85], v[36:37], v[68:69]
	v_cvt_pk_bf16_f32 v124, v34, v35
	v_cvt_pk_bf16_f32 v125, v36, v37
	global_store_dwordx2 v2, v[124:125], s[8:9] offset:1024
	v_pk_mul_f32 v[38:39], v[122:123], v[38:39]
	v_pk_mul_f32 v[38:39], v[22:23], v[38:39]
	v_pk_fma_f32 v[38:39], v[86:87], v[38:39], v[70:71]
	v_pk_mul_f32 v[40:41], v[122:123], v[40:41]
	v_pk_mul_f32 v[40:41], v[24:25], v[40:41]
	v_pk_fma_f32 v[40:41], v[88:89], v[40:41], v[72:73]
	v_cvt_pk_bf16_f32 v126, v38, v39
	v_cvt_pk_bf16_f32 v127, v40, v41
	global_store_dwordx2 v2, v[126:127], s[8:9] offset:1536

.LBB0_989:
	s_or_b64 exec, exec, s[0:1]
	v_readlane_b32 s0, v254, 23
	v_readlane_b32 s1, v254, 24
	s_and_b64 vcc, exec, s[0:1]
	v_readlane_b32 s12, v254, 47
	s_waitcnt lgkmcnt(0)
	s_barrier
	v_mbcnt_lo_u32_b32 v0, -1, 0
	v_mbcnt_hi_u32_b32 v0, -1, v0
	v_readlane_b32 s13, v254, 48
	s_cbranch_vccz .LBB0_992
	v_and_b32_e32 v0, 63, v0
	v_readlane_b32 s1, v254, 21
	v_lshlrev_b32_e32 v1, 4, v0
	v_lshlrev_b32_e32 v2, 3, v0
	v_mov_b32_e32 v3, 0x358637bd
	v_add_u32_e32 v4, 0x1000, v1
	s_lshl_b32 s1, s1, 4
	global_load_dwordx4 v[10:13], v1, s[58:59]
	global_load_dwordx4 v[14:17], v1, s[58:59] offset:1024
	global_load_dwordx4 v[18:21], v1, s[58:59] offset:2048
	global_load_dwordx4 v[22:25], v1, s[58:59] offset:3072
	s_lshl_b32 s0, s1, 12
	s_add_u32 s4, s68, s0
	s_addc_u32 s5, s69, 0
	s_ashr_i32 s0, s1, 12
	s_mul_i32 s0, s0, 0x6000
	s_add_i32 s0, s0, 0x3000
	s_add_u32 s6, s70, s0
	s_addc_u32 s7, s71, 0
	s_lshl_b32 s0, s1, 11
	s_add_u32 s8, s70, 0x13000000
	s_addc_u32 s9, s71, 0
	s_add_u32 s8, s8, s0
	s_addc_u32 s9, s9, 0
	global_load_dwordx4 v[26:29], v1, s[4:5] nt
	global_load_dwordx4 v[30:33], v1, s[4:5] offset:1024 nt
	global_load_dwordx4 v[34:37], v1, s[4:5] offset:2048 nt
	global_load_dwordx4 v[38:41], v1, s[4:5] offset:3072 nt
	s_add_u32 s4, s4, 0x1000
	s_addc_u32 s5, s5, 0
	global_load_dwordx4 v[58:61], v1, s[6:7]
	global_load_dwordx4 v[62:65], v1, s[6:7] offset:1024
	global_load_dwordx4 v[66:69], v1, s[6:7] offset:2048
	global_load_dwordx4 v[70:73], v1, s[6:7] offset:3072
	global_load_dwordx4 v[74:77], v4, s[6:7]
	global_load_dwordx4 v[78:81], v4, s[6:7] offset:1024
	global_load_dwordx4 v[82:85], v4, s[6:7] offset:2048
	global_load_dwordx4 v[86:89], v4, s[6:7] offset:3072
	global_load_dwordx4 v[42:45], v1, s[4:5] nt
	global_load_dwordx4 v[46:49], v1, s[4:5] offset:1024 nt
	global_load_dwordx4 v[50:53], v1, s[4:5] offset:2048 nt
	global_load_dwordx4 v[54:57], v1, s[4:5] offset:3072 nt
	s_add_u32 s4, s4, 0x1000
	s_addc_u32 s5, s5, 0
	global_load_dwordx4 v[90:93], v1, s[4:5] nt
	global_load_dwordx4 v[94:97], v1, s[4:5] offset:1024 nt
	global_load_dwordx4 v[98:101], v1, s[4:5] offset:2048 nt
	global_load_dwordx4 v[102:105], v1, s[4:5] offset:3072 nt
	s_add_u32 s4, s4, 0x1000
	s_addc_u32 s5, s5, 0
	s_waitcnt vmcnt(8)
	v_pk_add_f32 v[74:75], v[74:75], 1.0 op_sel_hi:[1,0]
	v_pk_add_f32 v[76:77], v[76:77], 1.0 op_sel_hi:[1,0]
	v_pk_add_f32 v[78:79], v[78:79], 1.0 op_sel_hi:[1,0]
	v_pk_add_f32 v[80:81], v[80:81], 1.0 op_sel_hi:[1,0]
	v_pk_add_f32 v[82:83], v[82:83], 1.0 op_sel_hi:[1,0]
	v_pk_add_f32 v[84:85], v[84:85], 1.0 op_sel_hi:[1,0]
	v_pk_add_f32 v[86:87], v[86:87], 1.0 op_sel_hi:[1,0]
	v_pk_add_f32 v[88:89], v[88:89], 1.0 op_sel_hi:[1,0]
	v_mul_f32_e32 v122, v26, v26
	v_fmac_f32_e32 v122, v27, v27
	v_fmac_f32_e32 v122, v28, v28
	v_fmac_f32_e32 v122, v29, v29
	v_mul_f32_e32 v123, v30, v30
	v_fmac_f32_e32 v123, v31, v31
	v_fmac_f32_e32 v123, v32, v32
	v_fmac_f32_e32 v123, v33, v33
	v_mul_f32_e32 v124, v34, v34
	v_fmac_f32_e32 v124, v35, v35
	v_fmac_f32_e32 v124, v36, v36
	v_fmac_f32_e32 v124, v37, v37
	v_mul_f32_e32 v125, v38, v38
	v_fmac_f32_e32 v125, v39, v39
	v_fmac_f32_e32 v125, v40, v40
	v_fmac_f32_e32 v125, v41, v41
	v_add_f32_e32 v122, v122, v123
	v_add_f32_e32 v124, v124, v125
	v_add_f32_e32 v122, v122, v124
	s_nop 1
	v_add_f32_dpp v122, v122, v122 quad_perm:[1,0,3,2] row_mask:0xf bank_mask:0xf bound_ctrl:1
	s_nop 1
	v_add_f32_dpp v122, v122, v122 quad_perm:[2,3,0,1] row_mask:0xf bank_mask:0xf bound_ctrl:1
	s_nop 1
	v_add_f32_dpp v122, v122, v122 row_half_mirror row_mask:0xf bank_mask:0xf bound_ctrl:1
	s_nop 1
	v_add_f32_dpp v122, v122, v122 row_mirror row_mask:0xf bank_mask:0xf bound_ctrl:1
	v_mov_b32_e32 v123, v122
	s_nop 1
	v_permlane16_swap_b32_e32 v122, v123
	v_add_f32_e32 v122, v122, v123
	v_mov_b32_e32 v123, v122
	s_nop 1
	v_permlane32_swap_b32_e32 v122, v123
	v_add_f32_e32 v122, v122, v123
	v_fmamk_f32 v122, v122, 0x3a800000, v3
	v_rsq_f32_e32 v122, v122
	s_nop 0
	v_mov_b32_e32 v123, v122
	v_pk_mul_f32 v[26:27], v[122:123], v[26:27]
	v_pk_mul_f32 v[26:27], v[10:11], v[26:27]
	v_pk_fma_f32 v[26:27], v[74:75], v[26:27], v[58:59]
	v_pk_mul_f32 v[28:29], v[122:123], v[28:29]
	v_pk_mul_f32 v[28:29], v[12:13], v[28:29]
	v_pk_fma_f32 v[28:29], v[76:77], v[28:29], v[60:61]
	v_cvt_pk_bf16_f32 v124, v26, v27
	v_cvt_pk_bf16_f32 v125, v28, v29
	global_store_dwordx2 v2, v[124:125], s[8:9]
	v_pk_mul_f32 v[30:31], v[122:123], v[30:31]
	v_pk_mul_f32 v[30:31], v[14:15], v[30:31]
	v_pk_fma_f32 v[30:31], v[78:79], v[30:31], v[62:63]
	v_pk_mul_f32 v[32:33], v[122:123], v[32:33]
	v_pk_mul_f32 v[32:33], v[16:17], v[32:33]
	v_pk_fma_f32 v[32:33], v[80:81], v[32:33], v[64:65]
	v_cvt_pk_bf16_f32 v126, v30, v31
	v_cvt_pk_bf16_f32 v127, v32, v33
	global_store_dwordx2 v2, v[126:127], s[8:9] offset:512
	v_pk_mul_f32 v[34:35], v[122:123], v[34:35]
	v_pk_mul_f32 v[34:35], v[18:19], v[34:35]
	v_pk_fma_f32 v[34:35], v[82:83], v[34:35], v[66:67]
	v_pk_mul_f32 v[36:37], v[122:123], v[36:37]
	v_pk_mul_f32 v[36:37], v[20:21], v[36:37]
	v_pk_fma_f32 v[36:37], v[84:85], v[36:37], v[68:69]
	v_cvt_pk_bf16_f32 v124, v34, v35
	v_cvt_pk_bf16_f32 v125, v36, v37
	global_store_dwordx2 v2, v[124:125], s[8:9] offset:1024
	v_pk_mul_f32 v[38:39], v[122:123], v[38:39]
	v_pk_mul_f32 v[38:39], v[22:23], v[38:39]
	v_pk_fma_f32 v[38:39], v[86:87], v[38:39], v[70:71]
	v_pk_mul_f32 v[40:41], v[122:123], v[40:41]
	v_pk_mul_f32 v[40:41], v[24:25], v[40:41]
	v_pk_fma_f32 v[40:41], v[88:89], v[40:41], v[72:73]
	v_cvt_pk_bf16_f32 v126, v38, v39
	v_cvt_pk_bf16_f32 v127, v40, v41
	global_store_dwordx2 v2, v[126:127], s[8:9] offset:1536
	s_add_u32 s8, s8, 0x800
	s_addc_u32 s9, s9, 0
	global_load_dwordx4 v[26:29], v1, s[4:5] nt
	global_load_dwordx4 v[30:33], v1, s[4:5] offset:1024 nt
	global_load_dwordx4 v[34:37], v1, s[4:5] offset:2048 nt
	global_load_dwordx4 v[38:41], v1, s[4:5] offset:3072 nt
	s_add_u32 s4, s4, 0x1000
	s_addc_u32 s5, s5, 0
	s_waitcnt vmcnt(12)
	v_mul_f32_e32 v122, v42, v42
	v_fmac_f32_e32 v122, v43, v43
	v_fmac_f32_e32 v122, v44, v44
	v_fmac_f32_e32 v122, v45, v45
	v_mul_f32_e32 v123, v46, v46
	v_fmac_f32_e32 v123, v47, v47
	v_fmac_f32_e32 v123, v48, v48
	v_fmac_f32_e32 v123, v49, v49
	v_mul_f32_e32 v124, v50, v50
	v_fmac_f32_e32 v124, v51, v51
	v_fmac_f32_e32 v124, v52, v52
	v_fmac_f32_e32 v124, v53, v53
	v_mul_f32_e32 v125, v54, v54
	v_fmac_f32_e32 v125, v55, v55
	v_fmac_f32_e32 v125, v56, v56
	v_fmac_f32_e32 v125, v57, v57
	v_add_f32_e32 v122, v122, v123
	v_add_f32_e32 v124, v124, v125
	v_add_f32_e32 v122, v122, v124
	s_nop 1
	v_add_f32_dpp v122, v122, v122 quad_perm:[1,0,3,2] row_mask:0xf bank_mask:0xf bound_ctrl:1
	s_nop 1
	v_add_f32_dpp v122, v122, v122 quad_perm:[2,3,0,1] row_mask:0xf bank_mask:0xf bound_ctrl:1
	s_nop 1
	v_add_f32_dpp v122, v122, v122 row_half_mirror row_mask:0xf bank_mask:0xf bound_ctrl:1
	s_nop 1
	v_add_f32_dpp v122, v122, v122 row_mirror row_mask:0xf bank_mask:0xf bound_ctrl:1
	v_mov_b32_e32 v123, v122
	s_nop 1
	v_permlane16_swap_b32_e32 v122, v123
	v_add_f32_e32 v122, v122, v123
	v_mov_b32_e32 v123, v122
	s_nop 1
	v_permlane32_swap_b32_e32 v122, v123
	v_add_f32_e32 v122, v122, v123
	v_fmamk_f32 v122, v122, 0x3a800000, v3
	v_rsq_f32_e32 v122, v122
	s_nop 0
	v_mov_b32_e32 v123, v122
	v_pk_mul_f32 v[42:43], v[122:123], v[42:43]
	v_pk_mul_f32 v[42:43], v[10:11], v[42:43]
	v_pk_fma_f32 v[42:43], v[74:75], v[42:43], v[58:59]
	v_pk_mul_f32 v[44:45], v[122:123], v[44:45]
	v_pk_mul_f32 v[44:45], v[12:13], v[44:45]
	v_pk_fma_f32 v[44:45], v[76:77], v[44:45], v[60:61]
	v_cvt_pk_bf16_f32 v124, v42, v43
	v_cvt_pk_bf16_f32 v125, v44, v45
	global_store_dwordx2 v2, v[124:125], s[8:9]
	v_pk_mul_f32 v[46:47], v[122:123], v[46:47]
	v_pk_mul_f32 v[46:47], v[14:15], v[46:47]
	v_pk_fma_f32 v[46:47], v[78:79], v[46:47], v[62:63]
	v_pk_mul_f32 v[48:49], v[122:123], v[48:49]
	v_pk_mul_f32 v[48:49], v[16:17], v[48:49]
	v_pk_fma_f32 v[48:49], v[80:81], v[48:49], v[64:65]
	v_cvt_pk_bf16_f32 v126, v46, v47
	v_cvt_pk_bf16_f32 v127, v48, v49
	global_store_dwordx2 v2, v[126:127], s[8:9] offset:512
	v_pk_mul_f32 v[50:51], v[122:123], v[50:51]
	v_pk_mul_f32 v[50:51], v[18:19], v[50:51]
	v_pk_fma_f32 v[50:51], v[82:83], v[50:51], v[66:67]
	v_pk_mul_f32 v[52:53], v[122:123], v[52:53]
	v_pk_mul_f32 v[52:53], v[20:21], v[52:53]
	v_pk_fma_f32 v[52:53], v[84:85], v[52:53], v[68:69]
	v_cvt_pk_bf16_f32 v124, v50, v51
	v_cvt_pk_bf16_f32 v125, v52, v53
	global_store_dwordx2 v2, v[124:125], s[8:9] offset:1024
	v_pk_mul_f32 v[54:55], v[122:123], v[54:55]
	v_pk_mul_f32 v[54:55], v[22:23], v[54:55]
	v_pk_fma_f32 v[54:55], v[86:87], v[54:55], v[70:71]
	v_pk_mul_f32 v[56:57], v[122:123], v[56:57]
	v_pk_mul_f32 v[56:57], v[24:25], v[56:57]
	v_pk_fma_f32 v[56:57], v[88:89], v[56:57], v[72:73]
	v_cvt_pk_bf16_f32 v126, v54, v55
	v_cvt_pk_bf16_f32 v127, v56, v57
	global_store_dwordx2 v2, v[126:127], s[8:9] offset:1536
	s_add_u32 s8, s8, 0x800
	s_addc_u32 s9, s9, 0
	global_load_dwordx4 v[42:45], v1, s[4:5] nt
	global_load_dwordx4 v[46:49], v1, s[4:5] offset:1024 nt
	global_load_dwordx4 v[50:53], v1, s[4:5] offset:2048 nt
	global_load_dwordx4 v[54:57], v1, s[4:5] offset:3072 nt
	s_add_u32 s4, s4, 0x1000
	s_addc_u32 s5, s5, 0
	s_waitcnt vmcnt(16)
	v_mul_f32_e32 v122, v90, v90
	v_fmac_f32_e32 v122, v91, v91
	v_fmac_f32_e32 v122, v92, v92
	v_fmac_f32_e32 v122, v93, v93
	v_mul_f32_e32 v123, v94, v94
	v_fmac_f32_e32 v123, v95, v95
	v_fmac_f32_e32 v123, v96, v96
	v_fmac_f32_e32 v123, v97, v97
	v_mul_f32_e32 v124, v98, v98
	v_fmac_f32_e32 v124, v99, v99
	v_fmac_f32_e32 v124, v100, v100
	v_fmac_f32_e32 v124, v101, v101
	v_mul_f32_e32 v125, v102, v102
	v_fmac_f32_e32 v125, v103, v103
	v_fmac_f32_e32 v125, v104, v104
	v_fmac_f32_e32 v125, v105, v105
	v_add_f32_e32 v122, v122, v123
	v_add_f32_e32 v124, v124, v125
	v_add_f32_e32 v122, v122, v124
	s_nop 1
	v_add_f32_dpp v122, v122, v122 quad_perm:[1,0,3,2] row_mask:0xf bank_mask:0xf bound_ctrl:1
	s_nop 1
	v_add_f32_dpp v122, v122, v122 quad_perm:[2,3,0,1] row_mask:0xf bank_mask:0xf bound_ctrl:1
	s_nop 1
	v_add_f32_dpp v122, v122, v122 row_half_mirror row_mask:0xf bank_mask:0xf bound_ctrl:1
	s_nop 1
	v_add_f32_dpp v122, v122, v122 row_mirror row_mask:0xf bank_mask:0xf bound_ctrl:1
	v_mov_b32_e32 v123, v122
	s_nop 1
	v_permlane16_swap_b32_e32 v122, v123
	v_add_f32_e32 v122, v122, v123
	v_mov_b32_e32 v123, v122
	s_nop 1
	v_permlane32_swap_b32_e32 v122, v123
	v_add_f32_e32 v122, v122, v123
	v_fmamk_f32 v122, v122, 0x3a800000, v3
	v_rsq_f32_e32 v122, v122
	s_nop 0
	v_mov_b32_e32 v123, v122
	v_pk_mul_f32 v[90:91], v[122:123], v[90:91]
	v_pk_mul_f32 v[90:91], v[10:11], v[90:91]
	v_pk_fma_f32 v[90:91], v[74:75], v[90:91], v[58:59]
	v_pk_mul_f32 v[92:93], v[122:123], v[92:93]
	v_pk_mul_f32 v[92:93], v[12:13], v[92:93]
	v_pk_fma_f32 v[92:93], v[76:77], v[92:93], v[60:61]
	v_cvt_pk_bf16_f32 v124, v90, v91
	v_cvt_pk_bf16_f32 v125, v92, v93
	global_store_dwordx2 v2, v[124:125], s[8:9]
	v_pk_mul_f32 v[94:95], v[122:123], v[94:95]
	v_pk_mul_f32 v[94:95], v[14:15], v[94:95]
	v_pk_fma_f32 v[94:95], v[78:79], v[94:95], v[62:63]
	v_pk_mul_f32 v[96:97], v[122:123], v[96:97]
	v_pk_mul_f32 v[96:97], v[16:17], v[96:97]
	v_pk_fma_f32 v[96:97], v[80:81], v[96:97], v[64:65]
	v_cvt_pk_bf16_f32 v126, v94, v95
	v_cvt_pk_bf16_f32 v127, v96, v97
	global_store_dwordx2 v2, v[126:127], s[8:9] offset:512
	v_pk_mul_f32 v[98:99], v[122:123], v[98:99]
	v_pk_mul_f32 v[98:99], v[18:19], v[98:99]
	v_pk_fma_f32 v[98:99], v[82:83], v[98:99], v[66:67]
	v_pk_mul_f32 v[100:101], v[122:123], v[100:101]
	v_pk_mul_f32 v[100:101], v[20:21], v[100:101]
	v_pk_fma_f32 v[100:101], v[84:85], v[100:101], v[68:69]
	v_cvt_pk_bf16_f32 v124, v98, v99
	v_cvt_pk_bf16_f32 v125, v100, v101
	global_store_dwordx2 v2, v[124:125], s[8:9] offset:1024
	v_pk_mul_f32 v[102:103], v[122:123], v[102:103]
	v_pk_mul_f32 v[102:103], v[22:23], v[102:103]
	v_pk_fma_f32 v[102:103], v[86:87], v[102:103], v[70:71]
	v_pk_mul_f32 v[104:105], v[122:123], v[104:105]
	v_pk_mul_f32 v[104:105], v[24:25], v[104:105]
	v_pk_fma_f32 v[104:105], v[88:89], v[104:105], v[72:73]
	v_cvt_pk_bf16_f32 v126, v102, v103
	v_cvt_pk_bf16_f32 v127, v104, v105
	global_store_dwordx2 v2, v[126:127], s[8:9] offset:1536
	s_add_u32 s8, s8, 0x800
	s_addc_u32 s9, s9, 0
	global_load_dwordx4 v[90:93], v1, s[4:5] nt
	global_load_dwordx4 v[94:97], v1, s[4:5] offset:1024 nt
	global_load_dwordx4 v[98:101], v1, s[4:5] offset:2048 nt
	global_load_dwordx4 v[102:105], v1, s[4:5] offset:3072 nt
	s_add_u32 s4, s4, 0x1000
	s_addc_u32 s5, s5, 0
	s_waitcnt vmcnt(16)
	v_mul_f32_e32 v122, v26, v26
	v_fmac_f32_e32 v122, v27, v27
	v_fmac_f32_e32 v122, v28, v28
	v_fmac_f32_e32 v122, v29, v29
	v_mul_f32_e32 v123, v30, v30
	v_fmac_f32_e32 v123, v31, v31
	v_fmac_f32_e32 v123, v32, v32
	v_fmac_f32_e32 v123, v33, v33
	v_mul_f32_e32 v124, v34, v34
	v_fmac_f32_e32 v124, v35, v35
	v_fmac_f32_e32 v124, v36, v36
	v_fmac_f32_e32 v124, v37, v37
	v_mul_f32_e32 v125, v38, v38
	v_fmac_f32_e32 v125, v39, v39
	v_fmac_f32_e32 v125, v40, v40
	v_fmac_f32_e32 v125, v41, v41
	v_add_f32_e32 v122, v122, v123
	v_add_f32_e32 v124, v124, v125
	v_add_f32_e32 v122, v122, v124
	s_nop 1
	v_add_f32_dpp v122, v122, v122 quad_perm:[1,0,3,2] row_mask:0xf bank_mask:0xf bound_ctrl:1
	s_nop 1
	v_add_f32_dpp v122, v122, v122 quad_perm:[2,3,0,1] row_mask:0xf bank_mask:0xf bound_ctrl:1
	s_nop 1
	v_add_f32_dpp v122, v122, v122 row_half_mirror row_mask:0xf bank_mask:0xf bound_ctrl:1
	s_nop 1
	v_add_f32_dpp v122, v122, v122 row_mirror row_mask:0xf bank_mask:0xf bound_ctrl:1
	v_mov_b32_e32 v123, v122
	s_nop 1
	v_permlane16_swap_b32_e32 v122, v123
	v_add_f32_e32 v122, v122, v123
	v_mov_b32_e32 v123, v122
	s_nop 1
	v_permlane32_swap_b32_e32 v122, v123
	v_add_f32_e32 v122, v122, v123
	v_fmamk_f32 v122, v122, 0x3a800000, v3
	v_rsq_f32_e32 v122, v122
	s_nop 0
	v_mov_b32_e32 v123, v122
	v_pk_mul_f32 v[26:27], v[122:123], v[26:27]
	v_pk_mul_f32 v[26:27], v[10:11], v[26:27]
	v_pk_fma_f32 v[26:27], v[74:75], v[26:27], v[58:59]
	v_pk_mul_f32 v[28:29], v[122:123], v[28:29]
	v_pk_mul_f32 v[28:29], v[12:13], v[28:29]
	v_pk_fma_f32 v[28:29], v[76:77], v[28:29], v[60:61]
	v_cvt_pk_bf16_f32 v124, v26, v27
	v_cvt_pk_bf16_f32 v125, v28, v29
	global_store_dwordx2 v2, v[124:125], s[8:9]
	v_pk_mul_f32 v[30:31], v[122:123], v[30:31]
	v_pk_mul_f32 v[30:31], v[14:15], v[30:31]
	v_pk_fma_f32 v[30:31], v[78:79], v[30:31], v[62:63]
	v_pk_mul_f32 v[32:33], v[122:123], v[32:33]
	v_pk_mul_f32 v[32:33], v[16:17], v[32:33]
	v_pk_fma_f32 v[32:33], v[80:81], v[32:33], v[64:65]
	v_cvt_pk_bf16_f32 v126, v30, v31
	v_cvt_pk_bf16_f32 v127, v32, v33
	global_store_dwordx2 v2, v[126:127], s[8:9] offset:512
	v_pk_mul_f32 v[34:35], v[122:123], v[34:35]
	v_pk_mul_f32 v[34:35], v[18:19], v[34:35]
	v_pk_fma_f32 v[34:35], v[82:83], v[34:35], v[66:67]
	v_pk_mul_f32 v[36:37], v[122:123], v[36:37]
	v_pk_mul_f32 v[36:37], v[20:21], v[36:37]
	v_pk_fma_f32 v[36:37], v[84:85], v[36:37], v[68:69]
	v_cvt_pk_bf16_f32 v124, v34, v35
	v_cvt_pk_bf16_f32 v125, v36, v37
	global_store_dwordx2 v2, v[124:125], s[8:9] offset:1024
	v_pk_mul_f32 v[38:39], v[122:123], v[38:39]
	v_pk_mul_f32 v[38:39], v[22:23], v[38:39]
	v_pk_fma_f32 v[38:39], v[86:87], v[38:39], v[70:71]
	v_pk_mul_f32 v[40:41], v[122:123], v[40:41]
	v_pk_mul_f32 v[40:41], v[24:25], v[40:41]
	v_pk_fma_f32 v[40:41], v[88:89], v[40:41], v[72:73]
	v_cvt_pk_bf16_f32 v126, v38, v39
	v_cvt_pk_bf16_f32 v127, v40, v41
	global_store_dwordx2 v2, v[126:127], s[8:9] offset:1536
	s_add_u32 s8, s8, 0x800
	s_addc_u32 s9, s9, 0
	global_load_dwordx4 v[26:29], v1, s[4:5] nt
	global_load_dwordx4 v[30:33], v1, s[4:5] offset:1024 nt
	global_load_dwordx4 v[34:37], v1, s[4:5] offset:2048 nt
	global_load_dwordx4 v[38:41], v1, s[4:5] offset:3072 nt
	s_add_u32 s4, s4, 0x1000
	s_addc_u32 s5, s5, 0
	s_waitcnt vmcnt(16)
	v_mul_f32_e32 v122, v42, v42
	v_fmac_f32_e32 v122, v43, v43
	v_fmac_f32_e32 v122, v44, v44
	v_fmac_f32_e32 v122, v45, v45
	v_mul_f32_e32 v123, v46, v46
	v_fmac_f32_e32 v123, v47, v47
	v_fmac_f32_e32 v123, v48, v48
	v_fmac_f32_e32 v123, v49, v49
	v_mul_f32_e32 v124, v50, v50
	v_fmac_f32_e32 v124, v51, v51
	v_fmac_f32_e32 v124, v52, v52
	v_fmac_f32_e32 v124, v53, v53
	v_mul_f32_e32 v125, v54, v54
	v_fmac_f32_e32 v125, v55, v55
	v_fmac_f32_e32 v125, v56, v56
	v_fmac_f32_e32 v125, v57, v57
	v_add_f32_e32 v122, v122, v123
	v_add_f32_e32 v124, v124, v125
	v_add_f32_e32 v122, v122, v124
	s_nop 1
	v_add_f32_dpp v122, v122, v122 quad_perm:[1,0,3,2] row_mask:0xf bank_mask:0xf bound_ctrl:1
	s_nop 1
	v_add_f32_dpp v122, v122, v122 quad_perm:[2,3,0,1] row_mask:0xf bank_mask:0xf bound_ctrl:1
	s_nop 1
	v_add_f32_dpp v122, v122, v122 row_half_mirror row_mask:0xf bank_mask:0xf bound_ctrl:1
	s_nop 1
	v_add_f32_dpp v122, v122, v122 row_mirror row_mask:0xf bank_mask:0xf bound_ctrl:1
	v_mov_b32_e32 v123, v122
	s_nop 1
	v_permlane16_swap_b32_e32 v122, v123
	v_add_f32_e32 v122, v122, v123
	v_mov_b32_e32 v123, v122
	s_nop 1
	v_permlane32_swap_b32_e32 v122, v123
	v_add_f32_e32 v122, v122, v123
	v_fmamk_f32 v122, v122, 0x3a800000, v3
	v_rsq_f32_e32 v122, v122
	s_nop 0
	v_mov_b32_e32 v123, v122
	v_pk_mul_f32 v[42:43], v[122:123], v[42:43]
	v_pk_mul_f32 v[42:43], v[10:11], v[42:43]
	v_pk_fma_f32 v[42:43], v[74:75], v[42:43], v[58:59]
	v_pk_mul_f32 v[44:45], v[122:123], v[44:45]
	v_pk_mul_f32 v[44:45], v[12:13], v[44:45]
	v_pk_fma_f32 v[44:45], v[76:77], v[44:45], v[60:61]
	v_cvt_pk_bf16_f32 v124, v42, v43
	v_cvt_pk_bf16_f32 v125, v44, v45
	global_store_dwordx2 v2, v[124:125], s[8:9]
	v_pk_mul_f32 v[46:47], v[122:123], v[46:47]
	v_pk_mul_f32 v[46:47], v[14:15], v[46:47]
	v_pk_fma_f32 v[46:47], v[78:79], v[46:47], v[62:63]
	v_pk_mul_f32 v[48:49], v[122:123], v[48:49]
	v_pk_mul_f32 v[48:49], v[16:17], v[48:49]
	v_pk_fma_f32 v[48:49], v[80:81], v[48:49], v[64:65]
	v_cvt_pk_bf16_f32 v126, v46, v47
	v_cvt_pk_bf16_f32 v127, v48, v49
	global_store_dwordx2 v2, v[126:127], s[8:9] offset:512
	v_pk_mul_f32 v[50:51], v[122:123], v[50:51]
	v_pk_mul_f32 v[50:51], v[18:19], v[50:51]
	v_pk_fma_f32 v[50:51], v[82:83], v[50:51], v[66:67]
	v_pk_mul_f32 v[52:53], v[122:123], v[52:53]
	v_pk_mul_f32 v[52:53], v[20:21], v[52:53]
	v_pk_fma_f32 v[52:53], v[84:85], v[52:53], v[68:69]
	v_cvt_pk_bf16_f32 v124, v50, v51
	v_cvt_pk_bf16_f32 v125, v52, v53
	global_store_dwordx2 v2, v[124:125], s[8:9] offset:1024
	v_pk_mul_f32 v[54:55], v[122:123], v[54:55]
	v_pk_mul_f32 v[54:55], v[22:23], v[54:55]
	v_pk_fma_f32 v[54:55], v[86:87], v[54:55], v[70:71]
	v_pk_mul_f32 v[56:57], v[122:123], v[56:57]
	v_pk_mul_f32 v[56:57], v[24:25], v[56:57]
	v_pk_fma_f32 v[56:57], v[88:89], v[56:57], v[72:73]
	v_cvt_pk_bf16_f32 v126, v54, v55
	v_cvt_pk_bf16_f32 v127, v56, v57
	global_store_dwordx2 v2, v[126:127], s[8:9] offset:1536
	s_add_u32 s8, s8, 0x800
	s_addc_u32 s9, s9, 0
	global_load_dwordx4 v[42:45], v1, s[4:5] nt
	global_load_dwordx4 v[46:49], v1, s[4:5] offset:1024 nt
	global_load_dwordx4 v[50:53], v1, s[4:5] offset:2048 nt
	global_load_dwordx4 v[54:57], v1, s[4:5] offset:3072 nt
	s_add_u32 s4, s4, 0x1000
	s_addc_u32 s5, s5, 0
	s_waitcnt vmcnt(16)
	v_mul_f32_e32 v122, v90, v90
	v_fmac_f32_e32 v122, v91, v91
	v_fmac_f32_e32 v122, v92, v92
	v_fmac_f32_e32 v122, v93, v93
	v_mul_f32_e32 v123, v94, v94
	v_fmac_f32_e32 v123, v95, v95
	v_fmac_f32_e32 v123, v96, v96
	v_fmac_f32_e32 v123, v97, v97
	v_mul_f32_e32 v124, v98, v98
	v_fmac_f32_e32 v124, v99, v99
	v_fmac_f32_e32 v124, v100, v100
	v_fmac_f32_e32 v124, v101, v101
	v_mul_f32_e32 v125, v102, v102
	v_fmac_f32_e32 v125, v103, v103
	v_fmac_f32_e32 v125, v104, v104
	v_fmac_f32_e32 v125, v105, v105
	v_add_f32_e32 v122, v122, v123
	v_add_f32_e32 v124, v124, v125
	v_add_f32_e32 v122, v122, v124
	s_nop 1
	v_add_f32_dpp v122, v122, v122 quad_perm:[1,0,3,2] row_mask:0xf bank_mask:0xf bound_ctrl:1
	s_nop 1
	v_add_f32_dpp v122, v122, v122 quad_perm:[2,3,0,1] row_mask:0xf bank_mask:0xf bound_ctrl:1
	s_nop 1
	v_add_f32_dpp v122, v122, v122 row_half_mirror row_mask:0xf bank_mask:0xf bound_ctrl:1
	s_nop 1
	v_add_f32_dpp v122, v122, v122 row_mirror row_mask:0xf bank_mask:0xf bound_ctrl:1
	v_mov_b32_e32 v123, v122
	s_nop 1
	v_permlane16_swap_b32_e32 v122, v123
	v_add_f32_e32 v122, v122, v123
	v_mov_b32_e32 v123, v122
	s_nop 1
	v_permlane32_swap_b32_e32 v122, v123
	v_add_f32_e32 v122, v122, v123
	v_fmamk_f32 v122, v122, 0x3a800000, v3
	v_rsq_f32_e32 v122, v122
	s_nop 0
	v_mov_b32_e32 v123, v122
	v_pk_mul_f32 v[90:91], v[122:123], v[90:91]
	v_pk_mul_f32 v[90:91], v[10:11], v[90:91]
	v_pk_fma_f32 v[90:91], v[74:75], v[90:91], v[58:59]
	v_pk_mul_f32 v[92:93], v[122:123], v[92:93]
	v_pk_mul_f32 v[92:93], v[12:13], v[92:93]
	v_pk_fma_f32 v[92:93], v[76:77], v[92:93], v[60:61]
	v_cvt_pk_bf16_f32 v124, v90, v91
	v_cvt_pk_bf16_f32 v125, v92, v93
	global_store_dwordx2 v2, v[124:125], s[8:9]
	v_pk_mul_f32 v[94:95], v[122:123], v[94:95]
	v_pk_mul_f32 v[94:95], v[14:15], v[94:95]
	v_pk_fma_f32 v[94:95], v[78:79], v[94:95], v[62:63]
	v_pk_mul_f32 v[96:97], v[122:123], v[96:97]
	v_pk_mul_f32 v[96:97], v[16:17], v[96:97]
	v_pk_fma_f32 v[96:97], v[80:81], v[96:97], v[64:65]
	v_cvt_pk_bf16_f32 v126, v94, v95
	v_cvt_pk_bf16_f32 v127, v96, v97
	global_store_dwordx2 v2, v[126:127], s[8:9] offset:512
	v_pk_mul_f32 v[98:99], v[122:123], v[98:99]
	v_pk_mul_f32 v[98:99], v[18:19], v[98:99]
	v_pk_fma_f32 v[98:99], v[82:83], v[98:99], v[66:67]
	v_pk_mul_f32 v[100:101], v[122:123], v[100:101]
	v_pk_mul_f32 v[100:101], v[20:21], v[100:101]
	v_pk_fma_f32 v[100:101], v[84:85], v[100:101], v[68:69]
	v_cvt_pk_bf16_f32 v124, v98, v99
	v_cvt_pk_bf16_f32 v125, v100, v101
	global_store_dwordx2 v2, v[124:125], s[8:9] offset:1024
	v_pk_mul_f32 v[102:103], v[122:123], v[102:103]
	v_pk_mul_f32 v[102:103], v[22:23], v[102:103]
	v_pk_fma_f32 v[102:103], v[86:87], v[102:103], v[70:71]
	v_pk_mul_f32 v[104:105], v[122:123], v[104:105]
	v_pk_mul_f32 v[104:105], v[24:25], v[104:105]
	v_pk_fma_f32 v[104:105], v[88:89], v[104:105], v[72:73]
	v_cvt_pk_bf16_f32 v126, v102, v103
	v_cvt_pk_bf16_f32 v127, v104, v105
	global_store_dwordx2 v2, v[126:127], s[8:9] offset:1536
	s_add_u32 s8, s8, 0x800
	s_addc_u32 s9, s9, 0
	global_load_dwordx4 v[90:93], v1, s[4:5] nt
	global_load_dwordx4 v[94:97], v1, s[4:5] offset:1024 nt
	global_load_dwordx4 v[98:101], v1, s[4:5] offset:2048 nt
	global_load_dwordx4 v[102:105], v1, s[4:5] offset:3072 nt
	s_add_u32 s4, s4, 0x1000
	s_addc_u32 s5, s5, 0
	s_waitcnt vmcnt(16)
	v_mul_f32_e32 v122, v26, v26
	v_fmac_f32_e32 v122, v27, v27
	v_fmac_f32_e32 v122, v28, v28
	v_fmac_f32_e32 v122, v29, v29
	v_mul_f32_e32 v123, v30, v30
	v_fmac_f32_e32 v123, v31, v31
	v_fmac_f32_e32 v123, v32, v32
	v_fmac_f32_e32 v123, v33, v33
	v_mul_f32_e32 v124, v34, v34
	v_fmac_f32_e32 v124, v35, v35
	v_fmac_f32_e32 v124, v36, v36
	v_fmac_f32_e32 v124, v37, v37
	v_mul_f32_e32 v125, v38, v38
	v_fmac_f32_e32 v125, v39, v39
	v_fmac_f32_e32 v125, v40, v40
	v_fmac_f32_e32 v125, v41, v41
	v_add_f32_e32 v122, v122, v123
	v_add_f32_e32 v124, v124, v125
	v_add_f32_e32 v122, v122, v124
	s_nop 1
	v_add_f32_dpp v122, v122, v122 quad_perm:[1,0,3,2] row_mask:0xf bank_mask:0xf bound_ctrl:1
	s_nop 1
	v_add_f32_dpp v122, v122, v122 quad_perm:[2,3,0,1] row_mask:0xf bank_mask:0xf bound_ctrl:1
	s_nop 1
	v_add_f32_dpp v122, v122, v122 row_half_mirror row_mask:0xf bank_mask:0xf bound_ctrl:1
	s_nop 1
	v_add_f32_dpp v122, v122, v122 row_mirror row_mask:0xf bank_mask:0xf bound_ctrl:1
	v_mov_b32_e32 v123, v122
	s_nop 1
	v_permlane16_swap_b32_e32 v122, v123
	v_add_f32_e32 v122, v122, v123
	v_mov_b32_e32 v123, v122
	s_nop 1
	v_permlane32_swap_b32_e32 v122, v123
	v_add_f32_e32 v122, v122, v123
	v_fmamk_f32 v122, v122, 0x3a800000, v3
	v_rsq_f32_e32 v122, v122
	s_nop 0
	v_mov_b32_e32 v123, v122
	v_pk_mul_f32 v[26:27], v[122:123], v[26:27]
	v_pk_mul_f32 v[26:27], v[10:11], v[26:27]
	v_pk_fma_f32 v[26:27], v[74:75], v[26:27], v[58:59]
	v_pk_mul_f32 v[28:29], v[122:123], v[28:29]
	v_pk_mul_f32 v[28:29], v[12:13], v[28:29]
	v_pk_fma_f32 v[28:29], v[76:77], v[28:29], v[60:61]
	v_cvt_pk_bf16_f32 v124, v26, v27
	v_cvt_pk_bf16_f32 v125, v28, v29
	global_store_dwordx2 v2, v[124:125], s[8:9]
	v_pk_mul_f32 v[30:31], v[122:123], v[30:31]
	v_pk_mul_f32 v[30:31], v[14:15], v[30:31]
	v_pk_fma_f32 v[30:31], v[78:79], v[30:31], v[62:63]
	v_pk_mul_f32 v[32:33], v[122:123], v[32:33]
	v_pk_mul_f32 v[32:33], v[16:17], v[32:33]
	v_pk_fma_f32 v[32:33], v[80:81], v[32:33], v[64:65]
	v_cvt_pk_bf16_f32 v126, v30, v31
	v_cvt_pk_bf16_f32 v127, v32, v33
	global_store_dwordx2 v2, v[126:127], s[8:9] offset:512
	v_pk_mul_f32 v[34:35], v[122:123], v[34:35]
	v_pk_mul_f32 v[34:35], v[18:19], v[34:35]
	v_pk_fma_f32 v[34:35], v[82:83], v[34:35], v[66:67]
	v_pk_mul_f32 v[36:37], v[122:123], v[36:37]
	v_pk_mul_f32 v[36:37], v[20:21], v[36:37]
	v_pk_fma_f32 v[36:37], v[84:85], v[36:37], v[68:69]
	v_cvt_pk_bf16_f32 v124, v34, v35
	v_cvt_pk_bf16_f32 v125, v36, v37
	global_store_dwordx2 v2, v[124:125], s[8:9] offset:1024
	v_pk_mul_f32 v[38:39], v[122:123], v[38:39]
	v_pk_mul_f32 v[38:39], v[22:23], v[38:39]
	v_pk_fma_f32 v[38:39], v[86:87], v[38:39], v[70:71]
	v_pk_mul_f32 v[40:41], v[122:123], v[40:41]
	v_pk_mul_f32 v[40:41], v[24:25], v[40:41]
	v_pk_fma_f32 v[40:41], v[88:89], v[40:41], v[72:73]
	v_cvt_pk_bf16_f32 v126, v38, v39
	v_cvt_pk_bf16_f32 v127, v40, v41
	global_store_dwordx2 v2, v[126:127], s[8:9] offset:1536
	s_add_u32 s8, s8, 0x800
	s_addc_u32 s9, s9, 0
	global_load_dwordx4 v[26:29], v1, s[4:5] nt
	global_load_dwordx4 v[30:33], v1, s[4:5] offset:1024 nt
	global_load_dwordx4 v[34:37], v1, s[4:5] offset:2048 nt
	global_load_dwordx4 v[38:41], v1, s[4:5] offset:3072 nt
	s_add_u32 s4, s4, 0x1000
	s_addc_u32 s5, s5, 0
	s_waitcnt vmcnt(16)
	v_mul_f32_e32 v122, v42, v42
	v_fmac_f32_e32 v122, v43, v43
	v_fmac_f32_e32 v122, v44, v44
	v_fmac_f32_e32 v122, v45, v45
	v_mul_f32_e32 v123, v46, v46
	v_fmac_f32_e32 v123, v47, v47
	v_fmac_f32_e32 v123, v48, v48
	v_fmac_f32_e32 v123, v49, v49
	v_mul_f32_e32 v124, v50, v50
	v_fmac_f32_e32 v124, v51, v51
	v_fmac_f32_e32 v124, v52, v52
	v_fmac_f32_e32 v124, v53, v53
	v_mul_f32_e32 v125, v54, v54
	v_fmac_f32_e32 v125, v55, v55
	v_fmac_f32_e32 v125, v56, v56
	v_fmac_f32_e32 v125, v57, v57
	v_add_f32_e32 v122, v122, v123
	v_add_f32_e32 v124, v124, v125
	v_add_f32_e32 v122, v122, v124
	s_nop 1
	v_add_f32_dpp v122, v122, v122 quad_perm:[1,0,3,2] row_mask:0xf bank_mask:0xf bound_ctrl:1
	s_nop 1
	v_add_f32_dpp v122, v122, v122 quad_perm:[2,3,0,1] row_mask:0xf bank_mask:0xf bound_ctrl:1
	s_nop 1
	v_add_f32_dpp v122, v122, v122 row_half_mirror row_mask:0xf bank_mask:0xf bound_ctrl:1
	s_nop 1
	v_add_f32_dpp v122, v122, v122 row_mirror row_mask:0xf bank_mask:0xf bound_ctrl:1
	v_mov_b32_e32 v123, v122
	s_nop 1
	v_permlane16_swap_b32_e32 v122, v123
	v_add_f32_e32 v122, v122, v123
	v_mov_b32_e32 v123, v122
	s_nop 1
	v_permlane32_swap_b32_e32 v122, v123
	v_add_f32_e32 v122, v122, v123
	v_fmamk_f32 v122, v122, 0x3a800000, v3
	v_rsq_f32_e32 v122, v122
	s_nop 0
	v_mov_b32_e32 v123, v122
	v_pk_mul_f32 v[42:43], v[122:123], v[42:43]
	v_pk_mul_f32 v[42:43], v[10:11], v[42:43]
	v_pk_fma_f32 v[42:43], v[74:75], v[42:43], v[58:59]
	v_pk_mul_f32 v[44:45], v[122:123], v[44:45]
	v_pk_mul_f32 v[44:45], v[12:13], v[44:45]
	v_pk_fma_f32 v[44:45], v[76:77], v[44:45], v[60:61]
	v_cvt_pk_bf16_f32 v124, v42, v43
	v_cvt_pk_bf16_f32 v125, v44, v45
	global_store_dwordx2 v2, v[124:125], s[8:9]
	v_pk_mul_f32 v[46:47], v[122:123], v[46:47]
	v_pk_mul_f32 v[46:47], v[14:15], v[46:47]
	v_pk_fma_f32 v[46:47], v[78:79], v[46:47], v[62:63]
	v_pk_mul_f32 v[48:49], v[122:123], v[48:49]
	v_pk_mul_f32 v[48:49], v[16:17], v[48:49]
	v_pk_fma_f32 v[48:49], v[80:81], v[48:49], v[64:65]
	v_cvt_pk_bf16_f32 v126, v46, v47
	v_cvt_pk_bf16_f32 v127, v48, v49
	global_store_dwordx2 v2, v[126:127], s[8:9] offset:512
	v_pk_mul_f32 v[50:51], v[122:123], v[50:51]
	v_pk_mul_f32 v[50:51], v[18:19], v[50:51]
	v_pk_fma_f32 v[50:51], v[82:83], v[50:51], v[66:67]
	v_pk_mul_f32 v[52:53], v[122:123], v[52:53]
	v_pk_mul_f32 v[52:53], v[20:21], v[52:53]
	v_pk_fma_f32 v[52:53], v[84:85], v[52:53], v[68:69]
	v_cvt_pk_bf16_f32 v124, v50, v51
	v_cvt_pk_bf16_f32 v125, v52, v53
	global_store_dwordx2 v2, v[124:125], s[8:9] offset:1024
	v_pk_mul_f32 v[54:55], v[122:123], v[54:55]
	v_pk_mul_f32 v[54:55], v[22:23], v[54:55]
	v_pk_fma_f32 v[54:55], v[86:87], v[54:55], v[70:71]
	v_pk_mul_f32 v[56:57], v[122:123], v[56:57]
	v_pk_mul_f32 v[56:57], v[24:25], v[56:57]
	v_pk_fma_f32 v[56:57], v[88:89], v[56:57], v[72:73]
	v_cvt_pk_bf16_f32 v126, v54, v55
	v_cvt_pk_bf16_f32 v127, v56, v57
	global_store_dwordx2 v2, v[126:127], s[8:9] offset:1536
	s_add_u32 s8, s8, 0x800
	s_addc_u32 s9, s9, 0
	global_load_dwordx4 v[42:45], v1, s[4:5] nt
	global_load_dwordx4 v[46:49], v1, s[4:5] offset:1024 nt
	global_load_dwordx4 v[50:53], v1, s[4:5] offset:2048 nt
	global_load_dwordx4 v[54:57], v1, s[4:5] offset:3072 nt
	s_add_u32 s4, s4, 0x1000
	s_addc_u32 s5, s5, 0
	s_waitcnt vmcnt(16)
	v_mul_f32_e32 v122, v90, v90
	v_fmac_f32_e32 v122, v91, v91
	v_fmac_f32_e32 v122, v92, v92
	v_fmac_f32_e32 v122, v93, v93
	v_mul_f32_e32 v123, v94, v94
	v_fmac_f32_e32 v123, v95, v95
	v_fmac_f32_e32 v123, v96, v96
	v_fmac_f32_e32 v123, v97, v97
	v_mul_f32_e32 v124, v98, v98
	v_fmac_f32_e32 v124, v99, v99
	v_fmac_f32_e32 v124, v100, v100
	v_fmac_f32_e32 v124, v101, v101
	v_mul_f32_e32 v125, v102, v102
	v_fmac_f32_e32 v125, v103, v103
	v_fmac_f32_e32 v125, v104, v104
	v_fmac_f32_e32 v125, v105, v105
	v_add_f32_e32 v122, v122, v123
	v_add_f32_e32 v124, v124, v125
	v_add_f32_e32 v122, v122, v124
	s_nop 1
	v_add_f32_dpp v122, v122, v122 quad_perm:[1,0,3,2] row_mask:0xf bank_mask:0xf bound_ctrl:1
	s_nop 1
	v_add_f32_dpp v122, v122, v122 quad_perm:[2,3,0,1] row_mask:0xf bank_mask:0xf bound_ctrl:1
	s_nop 1
	v_add_f32_dpp v122, v122, v122 row_half_mirror row_mask:0xf bank_mask:0xf bound_ctrl:1
	s_nop 1
	v_add_f32_dpp v122, v122, v122 row_mirror row_mask:0xf bank_mask:0xf bound_ctrl:1
	v_mov_b32_e32 v123, v122
	s_nop 1
	v_permlane16_swap_b32_e32 v122, v123
	v_add_f32_e32 v122, v122, v123
	v_mov_b32_e32 v123, v122
	s_nop 1
	v_permlane32_swap_b32_e32 v122, v123
	v_add_f32_e32 v122, v122, v123
	v_fmamk_f32 v122, v122, 0x3a800000, v3
	v_rsq_f32_e32 v122, v122
	s_nop 0
	v_mov_b32_e32 v123, v122
	v_pk_mul_f32 v[90:91], v[122:123], v[90:91]
	v_pk_mul_f32 v[90:91], v[10:11], v[90:91]
	v_pk_fma_f32 v[90:91], v[74:75], v[90:91], v[58:59]
	v_pk_mul_f32 v[92:93], v[122:123], v[92:93]
	v_pk_mul_f32 v[92:93], v[12:13], v[92:93]
	v_pk_fma_f32 v[92:93], v[76:77], v[92:93], v[60:61]
	v_cvt_pk_bf16_f32 v124, v90, v91
	v_cvt_pk_bf16_f32 v125, v92, v93
	global_store_dwordx2 v2, v[124:125], s[8:9]
	v_pk_mul_f32 v[94:95], v[122:123], v[94:95]
	v_pk_mul_f32 v[94:95], v[14:15], v[94:95]
	v_pk_fma_f32 v[94:95], v[78:79], v[94:95], v[62:63]
	v_pk_mul_f32 v[96:97], v[122:123], v[96:97]
	v_pk_mul_f32 v[96:97], v[16:17], v[96:97]
	v_pk_fma_f32 v[96:97], v[80:81], v[96:97], v[64:65]
	v_cvt_pk_bf16_f32 v126, v94, v95
	v_cvt_pk_bf16_f32 v127, v96, v97
	global_store_dwordx2 v2, v[126:127], s[8:9] offset:512
	v_pk_mul_f32 v[98:99], v[122:123], v[98:99]
	v_pk_mul_f32 v[98:99], v[18:19], v[98:99]
	v_pk_fma_f32 v[98:99], v[82:83], v[98:99], v[66:67]
	v_pk_mul_f32 v[100:101], v[122:123], v[100:101]
	v_pk_mul_f32 v[100:101], v[20:21], v[100:101]
	v_pk_fma_f32 v[100:101], v[84:85], v[100:101], v[68:69]
	v_cvt_pk_bf16_f32 v124, v98, v99
	v_cvt_pk_bf16_f32 v125, v100, v101
	global_store_dwordx2 v2, v[124:125], s[8:9] offset:1024
	v_pk_mul_f32 v[102:103], v[122:123], v[102:103]
	v_pk_mul_f32 v[102:103], v[22:23], v[102:103]
	v_pk_fma_f32 v[102:103], v[86:87], v[102:103], v[70:71]
	v_pk_mul_f32 v[104:105], v[122:123], v[104:105]
	v_pk_mul_f32 v[104:105], v[24:25], v[104:105]
	v_pk_fma_f32 v[104:105], v[88:89], v[104:105], v[72:73]
	v_cvt_pk_bf16_f32 v126, v102, v103
	v_cvt_pk_bf16_f32 v127, v104, v105
	global_store_dwordx2 v2, v[126:127], s[8:9] offset:1536
	s_add_u32 s8, s8, 0x800
	s_addc_u32 s9, s9, 0
	global_load_dwordx4 v[90:93], v1, s[4:5] nt
	global_load_dwordx4 v[94:97], v1, s[4:5] offset:1024 nt
	global_load_dwordx4 v[98:101], v1, s[4:5] offset:2048 nt
	global_load_dwordx4 v[102:105], v1, s[4:5] offset:3072 nt
	s_add_u32 s4, s4, 0x1000
	s_addc_u32 s5, s5, 0
	s_waitcnt vmcnt(16)
	v_mul_f32_e32 v122, v26, v26
	v_fmac_f32_e32 v122, v27, v27
	v_fmac_f32_e32 v122, v28, v28
	v_fmac_f32_e32 v122, v29, v29
	v_mul_f32_e32 v123, v30, v30
	v_fmac_f32_e32 v123, v31, v31
	v_fmac_f32_e32 v123, v32, v32
	v_fmac_f32_e32 v123, v33, v33
	v_mul_f32_e32 v124, v34, v34
	v_fmac_f32_e32 v124, v35, v35
	v_fmac_f32_e32 v124, v36, v36
	v_fmac_f32_e32 v124, v37, v37
	v_mul_f32_e32 v125, v38, v38
	v_fmac_f32_e32 v125, v39, v39
	v_fmac_f32_e32 v125, v40, v40
	v_fmac_f32_e32 v125, v41, v41
	v_add_f32_e32 v122, v122, v123
	v_add_f32_e32 v124, v124, v125
	v_add_f32_e32 v122, v122, v124
	s_nop 1
	v_add_f32_dpp v122, v122, v122 quad_perm:[1,0,3,2] row_mask:0xf bank_mask:0xf bound_ctrl:1
	s_nop 1
	v_add_f32_dpp v122, v122, v122 quad_perm:[2,3,0,1] row_mask:0xf bank_mask:0xf bound_ctrl:1
	s_nop 1
	v_add_f32_dpp v122, v122, v122 row_half_mirror row_mask:0xf bank_mask:0xf bound_ctrl:1
	s_nop 1
	v_add_f32_dpp v122, v122, v122 row_mirror row_mask:0xf bank_mask:0xf bound_ctrl:1
	v_mov_b32_e32 v123, v122
	s_nop 1
	v_permlane16_swap_b32_e32 v122, v123
	v_add_f32_e32 v122, v122, v123
	v_mov_b32_e32 v123, v122
	s_nop 1
	v_permlane32_swap_b32_e32 v122, v123
	v_add_f32_e32 v122, v122, v123
	v_fmamk_f32 v122, v122, 0x3a800000, v3
	v_rsq_f32_e32 v122, v122
	s_nop 0
	v_mov_b32_e32 v123, v122
	v_pk_mul_f32 v[26:27], v[122:123], v[26:27]
	v_pk_mul_f32 v[26:27], v[10:11], v[26:27]
	v_pk_fma_f32 v[26:27], v[74:75], v[26:27], v[58:59]
	v_pk_mul_f32 v[28:29], v[122:123], v[28:29]
	v_pk_mul_f32 v[28:29], v[12:13], v[28:29]
	v_pk_fma_f32 v[28:29], v[76:77], v[28:29], v[60:61]
	v_cvt_pk_bf16_f32 v124, v26, v27
	v_cvt_pk_bf16_f32 v125, v28, v29
	global_store_dwordx2 v2, v[124:125], s[8:9]
	v_pk_mul_f32 v[30:31], v[122:123], v[30:31]
	v_pk_mul_f32 v[30:31], v[14:15], v[30:31]
	v_pk_fma_f32 v[30:31], v[78:79], v[30:31], v[62:63]
	v_pk_mul_f32 v[32:33], v[122:123], v[32:33]
	v_pk_mul_f32 v[32:33], v[16:17], v[32:33]
	v_pk_fma_f32 v[32:33], v[80:81], v[32:33], v[64:65]
	v_cvt_pk_bf16_f32 v126, v30, v31
	v_cvt_pk_bf16_f32 v127, v32, v33
	global_store_dwordx2 v2, v[126:127], s[8:9] offset:512
	v_pk_mul_f32 v[34:35], v[122:123], v[34:35]
	v_pk_mul_f32 v[34:35], v[18:19], v[34:35]
	v_pk_fma_f32 v[34:35], v[82:83], v[34:35], v[66:67]
	v_pk_mul_f32 v[36:37], v[122:123], v[36:37]
	v_pk_mul_f32 v[36:37], v[20:21], v[36:37]
	v_pk_fma_f32 v[36:37], v[84:85], v[36:37], v[68:69]
	v_cvt_pk_bf16_f32 v124, v34, v35
	v_cvt_pk_bf16_f32 v125, v36, v37
	global_store_dwordx2 v2, v[124:125], s[8:9] offset:1024
	v_pk_mul_f32 v[38:39], v[122:123], v[38:39]
	v_pk_mul_f32 v[38:39], v[22:23], v[38:39]
	v_pk_fma_f32 v[38:39], v[86:87], v[38:39], v[70:71]
	v_pk_mul_f32 v[40:41], v[122:123], v[40:41]
	v_pk_mul_f32 v[40:41], v[24:25], v[40:41]
	v_pk_fma_f32 v[40:41], v[88:89], v[40:41], v[72:73]
	v_cvt_pk_bf16_f32 v126, v38, v39
	v_cvt_pk_bf16_f32 v127, v40, v41
	global_store_dwordx2 v2, v[126:127], s[8:9] offset:1536
	s_add_u32 s8, s8, 0x800
	s_addc_u32 s9, s9, 0
	global_load_dwordx4 v[26:29], v1, s[4:5] nt
	global_load_dwordx4 v[30:33], v1, s[4:5] offset:1024 nt
	global_load_dwordx4 v[34:37], v1, s[4:5] offset:2048 nt
	global_load_dwordx4 v[38:41], v1, s[4:5] offset:3072 nt
	s_add_u32 s4, s4, 0x1000
	s_addc_u32 s5, s5, 0
	s_waitcnt vmcnt(16)
	v_mul_f32_e32 v122, v42, v42
	v_fmac_f32_e32 v122, v43, v43
	v_fmac_f32_e32 v122, v44, v44
	v_fmac_f32_e32 v122, v45, v45
	v_mul_f32_e32 v123, v46, v46
	v_fmac_f32_e32 v123, v47, v47
	v_fmac_f32_e32 v123, v48, v48
	v_fmac_f32_e32 v123, v49, v49
	v_mul_f32_e32 v124, v50, v50
	v_fmac_f32_e32 v124, v51, v51
	v_fmac_f32_e32 v124, v52, v52
	v_fmac_f32_e32 v124, v53, v53
	v_mul_f32_e32 v125, v54, v54
	v_fmac_f32_e32 v125, v55, v55
	v_fmac_f32_e32 v125, v56, v56
	v_fmac_f32_e32 v125, v57, v57
	v_add_f32_e32 v122, v122, v123
	v_add_f32_e32 v124, v124, v125
	v_add_f32_e32 v122, v122, v124
	s_nop 1
	v_add_f32_dpp v122, v122, v122 quad_perm:[1,0,3,2] row_mask:0xf bank_mask:0xf bound_ctrl:1
	s_nop 1
	v_add_f32_dpp v122, v122, v122 quad_perm:[2,3,0,1] row_mask:0xf bank_mask:0xf bound_ctrl:1
	s_nop 1
	v_add_f32_dpp v122, v122, v122 row_half_mirror row_mask:0xf bank_mask:0xf bound_ctrl:1
	s_nop 1
	v_add_f32_dpp v122, v122, v122 row_mirror row_mask:0xf bank_mask:0xf bound_ctrl:1
	v_mov_b32_e32 v123, v122
	s_nop 1
	v_permlane16_swap_b32_e32 v122, v123
	v_add_f32_e32 v122, v122, v123
	v_mov_b32_e32 v123, v122
	s_nop 1
	v_permlane32_swap_b32_e32 v122, v123
	v_add_f32_e32 v122, v122, v123
	v_fmamk_f32 v122, v122, 0x3a800000, v3
	v_rsq_f32_e32 v122, v122
	s_nop 0
	v_mov_b32_e32 v123, v122
	v_pk_mul_f32 v[42:43], v[122:123], v[42:43]
	v_pk_mul_f32 v[42:43], v[10:11], v[42:43]
	v_pk_fma_f32 v[42:43], v[74:75], v[42:43], v[58:59]
	v_pk_mul_f32 v[44:45], v[122:123], v[44:45]
	v_pk_mul_f32 v[44:45], v[12:13], v[44:45]
	v_pk_fma_f32 v[44:45], v[76:77], v[44:45], v[60:61]
	v_cvt_pk_bf16_f32 v124, v42, v43
	v_cvt_pk_bf16_f32 v125, v44, v45
	global_store_dwordx2 v2, v[124:125], s[8:9]
	v_pk_mul_f32 v[46:47], v[122:123], v[46:47]
	v_pk_mul_f32 v[46:47], v[14:15], v[46:47]
	v_pk_fma_f32 v[46:47], v[78:79], v[46:47], v[62:63]
	v_pk_mul_f32 v[48:49], v[122:123], v[48:49]
	v_pk_mul_f32 v[48:49], v[16:17], v[48:49]
	v_pk_fma_f32 v[48:49], v[80:81], v[48:49], v[64:65]
	v_cvt_pk_bf16_f32 v126, v46, v47
	v_cvt_pk_bf16_f32 v127, v48, v49
	global_store_dwordx2 v2, v[126:127], s[8:9] offset:512
	v_pk_mul_f32 v[50:51], v[122:123], v[50:51]
	v_pk_mul_f32 v[50:51], v[18:19], v[50:51]
	v_pk_fma_f32 v[50:51], v[82:83], v[50:51], v[66:67]
	v_pk_mul_f32 v[52:53], v[122:123], v[52:53]
	v_pk_mul_f32 v[52:53], v[20:21], v[52:53]
	v_pk_fma_f32 v[52:53], v[84:85], v[52:53], v[68:69]
	v_cvt_pk_bf16_f32 v124, v50, v51
	v_cvt_pk_bf16_f32 v125, v52, v53
	global_store_dwordx2 v2, v[124:125], s[8:9] offset:1024
	v_pk_mul_f32 v[54:55], v[122:123], v[54:55]
	v_pk_mul_f32 v[54:55], v[22:23], v[54:55]
	v_pk_fma_f32 v[54:55], v[86:87], v[54:55], v[70:71]
	v_pk_mul_f32 v[56:57], v[122:123], v[56:57]
	v_pk_mul_f32 v[56:57], v[24:25], v[56:57]
	v_pk_fma_f32 v[56:57], v[88:89], v[56:57], v[72:73]
	v_cvt_pk_bf16_f32 v126, v54, v55
	v_cvt_pk_bf16_f32 v127, v56, v57
	global_store_dwordx2 v2, v[126:127], s[8:9] offset:1536
	s_add_u32 s8, s8, 0x800
	s_addc_u32 s9, s9, 0
	global_load_dwordx4 v[42:45], v1, s[4:5] nt
	global_load_dwordx4 v[46:49], v1, s[4:5] offset:1024 nt
	global_load_dwordx4 v[50:53], v1, s[4:5] offset:2048 nt
	global_load_dwordx4 v[54:57], v1, s[4:5] offset:3072 nt
	s_add_u32 s4, s4, 0x1000
	s_addc_u32 s5, s5, 0
	s_waitcnt vmcnt(16)
	v_mul_f32_e32 v122, v90, v90
	v_fmac_f32_e32 v122, v91, v91
	v_fmac_f32_e32 v122, v92, v92
	v_fmac_f32_e32 v122, v93, v93
	v_mul_f32_e32 v123, v94, v94
	v_fmac_f32_e32 v123, v95, v95
	v_fmac_f32_e32 v123, v96, v96
	v_fmac_f32_e32 v123, v97, v97
	v_mul_f32_e32 v124, v98, v98
	v_fmac_f32_e32 v124, v99, v99
	v_fmac_f32_e32 v124, v100, v100
	v_fmac_f32_e32 v124, v101, v101
	v_mul_f32_e32 v125, v102, v102
	v_fmac_f32_e32 v125, v103, v103
	v_fmac_f32_e32 v125, v104, v104
	v_fmac_f32_e32 v125, v105, v105
	v_add_f32_e32 v122, v122, v123
	v_add_f32_e32 v124, v124, v125
	v_add_f32_e32 v122, v122, v124
	s_nop 1
	v_add_f32_dpp v122, v122, v122 quad_perm:[1,0,3,2] row_mask:0xf bank_mask:0xf bound_ctrl:1
	s_nop 1
	v_add_f32_dpp v122, v122, v122 quad_perm:[2,3,0,1] row_mask:0xf bank_mask:0xf bound_ctrl:1
	s_nop 1
	v_add_f32_dpp v122, v122, v122 row_half_mirror row_mask:0xf bank_mask:0xf bound_ctrl:1
	s_nop 1
	v_add_f32_dpp v122, v122, v122 row_mirror row_mask:0xf bank_mask:0xf bound_ctrl:1
	v_mov_b32_e32 v123, v122
	s_nop 1
	v_permlane16_swap_b32_e32 v122, v123
	v_add_f32_e32 v122, v122, v123
	v_mov_b32_e32 v123, v122
	s_nop 1
	v_permlane32_swap_b32_e32 v122, v123
	v_add_f32_e32 v122, v122, v123
	v_fmamk_f32 v122, v122, 0x3a800000, v3
	v_rsq_f32_e32 v122, v122
	s_nop 0
	v_mov_b32_e32 v123, v122
	v_pk_mul_f32 v[90:91], v[122:123], v[90:91]
	v_pk_mul_f32 v[90:91], v[10:11], v[90:91]
	v_pk_fma_f32 v[90:91], v[74:75], v[90:91], v[58:59]
	v_pk_mul_f32 v[92:93], v[122:123], v[92:93]
	v_pk_mul_f32 v[92:93], v[12:13], v[92:93]
	v_pk_fma_f32 v[92:93], v[76:77], v[92:93], v[60:61]
	v_cvt_pk_bf16_f32 v124, v90, v91
	v_cvt_pk_bf16_f32 v125, v92, v93
	global_store_dwordx2 v2, v[124:125], s[8:9]
	v_pk_mul_f32 v[94:95], v[122:123], v[94:95]
	v_pk_mul_f32 v[94:95], v[14:15], v[94:95]
	v_pk_fma_f32 v[94:95], v[78:79], v[94:95], v[62:63]
	v_pk_mul_f32 v[96:97], v[122:123], v[96:97]
	v_pk_mul_f32 v[96:97], v[16:17], v[96:97]
	v_pk_fma_f32 v[96:97], v[80:81], v[96:97], v[64:65]
	v_cvt_pk_bf16_f32 v126, v94, v95
	v_cvt_pk_bf16_f32 v127, v96, v97
	global_store_dwordx2 v2, v[126:127], s[8:9] offset:512
	v_pk_mul_f32 v[98:99], v[122:123], v[98:99]
	v_pk_mul_f32 v[98:99], v[18:19], v[98:99]
	v_pk_fma_f32 v[98:99], v[82:83], v[98:99], v[66:67]
	v_pk_mul_f32 v[100:101], v[122:123], v[100:101]
	v_pk_mul_f32 v[100:101], v[20:21], v[100:101]
	v_pk_fma_f32 v[100:101], v[84:85], v[100:101], v[68:69]
	v_cvt_pk_bf16_f32 v124, v98, v99
	v_cvt_pk_bf16_f32 v125, v100, v101
	global_store_dwordx2 v2, v[124:125], s[8:9] offset:1024
	v_pk_mul_f32 v[102:103], v[122:123], v[102:103]
	v_pk_mul_f32 v[102:103], v[22:23], v[102:103]
	v_pk_fma_f32 v[102:103], v[86:87], v[102:103], v[70:71]
	v_pk_mul_f32 v[104:105], v[122:123], v[104:105]
	v_pk_mul_f32 v[104:105], v[24:25], v[104:105]
	v_pk_fma_f32 v[104:105], v[88:89], v[104:105], v[72:73]
	v_cvt_pk_bf16_f32 v126, v102, v103
	v_cvt_pk_bf16_f32 v127, v104, v105
	global_store_dwordx2 v2, v[126:127], s[8:9] offset:1536
	s_add_u32 s8, s8, 0x800
	s_addc_u32 s9, s9, 0
	global_load_dwordx4 v[90:93], v1, s[4:5] nt
	global_load_dwordx4 v[94:97], v1, s[4:5] offset:1024 nt
	global_load_dwordx4 v[98:101], v1, s[4:5] offset:2048 nt
	global_load_dwordx4 v[102:105], v1, s[4:5] offset:3072 nt
	s_add_u32 s4, s4, 0x1000
	s_addc_u32 s5, s5, 0
	s_waitcnt vmcnt(16)
	v_mul_f32_e32 v122, v26, v26
	v_fmac_f32_e32 v122, v27, v27
	v_fmac_f32_e32 v122, v28, v28
	v_fmac_f32_e32 v122, v29, v29
	v_mul_f32_e32 v123, v30, v30
	v_fmac_f32_e32 v123, v31, v31
	v_fmac_f32_e32 v123, v32, v32
	v_fmac_f32_e32 v123, v33, v33
	v_mul_f32_e32 v124, v34, v34
	v_fmac_f32_e32 v124, v35, v35
	v_fmac_f32_e32 v124, v36, v36
	v_fmac_f32_e32 v124, v37, v37
	v_mul_f32_e32 v125, v38, v38
	v_fmac_f32_e32 v125, v39, v39
	v_fmac_f32_e32 v125, v40, v40
	v_fmac_f32_e32 v125, v41, v41
	v_add_f32_e32 v122, v122, v123
	v_add_f32_e32 v124, v124, v125
	v_add_f32_e32 v122, v122, v124
	s_nop 1
	v_add_f32_dpp v122, v122, v122 quad_perm:[1,0,3,2] row_mask:0xf bank_mask:0xf bound_ctrl:1
	s_nop 1
	v_add_f32_dpp v122, v122, v122 quad_perm:[2,3,0,1] row_mask:0xf bank_mask:0xf bound_ctrl:1
	s_nop 1
	v_add_f32_dpp v122, v122, v122 row_half_mirror row_mask:0xf bank_mask:0xf bound_ctrl:1
	s_nop 1
	v_add_f32_dpp v122, v122, v122 row_mirror row_mask:0xf bank_mask:0xf bound_ctrl:1
	v_mov_b32_e32 v123, v122
	s_nop 1
	v_permlane16_swap_b32_e32 v122, v123
	v_add_f32_e32 v122, v122, v123
	v_mov_b32_e32 v123, v122
	s_nop 1
	v_permlane32_swap_b32_e32 v122, v123
	v_add_f32_e32 v122, v122, v123
	v_fmamk_f32 v122, v122, 0x3a800000, v3
	v_rsq_f32_e32 v122, v122
	s_nop 0
	v_mov_b32_e32 v123, v122
	v_pk_mul_f32 v[26:27], v[122:123], v[26:27]
	v_pk_mul_f32 v[26:27], v[10:11], v[26:27]
	v_pk_fma_f32 v[26:27], v[74:75], v[26:27], v[58:59]
	v_pk_mul_f32 v[28:29], v[122:123], v[28:29]
	v_pk_mul_f32 v[28:29], v[12:13], v[28:29]
	v_pk_fma_f32 v[28:29], v[76:77], v[28:29], v[60:61]
	v_cvt_pk_bf16_f32 v124, v26, v27
	v_cvt_pk_bf16_f32 v125, v28, v29
	global_store_dwordx2 v2, v[124:125], s[8:9]
	v_pk_mul_f32 v[30:31], v[122:123], v[30:31]
	v_pk_mul_f32 v[30:31], v[14:15], v[30:31]
	v_pk_fma_f32 v[30:31], v[78:79], v[30:31], v[62:63]
	v_pk_mul_f32 v[32:33], v[122:123], v[32:33]
	v_pk_mul_f32 v[32:33], v[16:17], v[32:33]
	v_pk_fma_f32 v[32:33], v[80:81], v[32:33], v[64:65]
	v_cvt_pk_bf16_f32 v126, v30, v31
	v_cvt_pk_bf16_f32 v127, v32, v33
	global_store_dwordx2 v2, v[126:127], s[8:9] offset:512
	v_pk_mul_f32 v[34:35], v[122:123], v[34:35]
	v_pk_mul_f32 v[34:35], v[18:19], v[34:35]
	v_pk_fma_f32 v[34:35], v[82:83], v[34:35], v[66:67]
	v_pk_mul_f32 v[36:37], v[122:123], v[36:37]
	v_pk_mul_f32 v[36:37], v[20:21], v[36:37]
	v_pk_fma_f32 v[36:37], v[84:85], v[36:37], v[68:69]
	v_cvt_pk_bf16_f32 v124, v34, v35
	v_cvt_pk_bf16_f32 v125, v36, v37
	global_store_dwordx2 v2, v[124:125], s[8:9] offset:1024
	v_pk_mul_f32 v[38:39], v[122:123], v[38:39]
	v_pk_mul_f32 v[38:39], v[22:23], v[38:39]
	v_pk_fma_f32 v[38:39], v[86:87], v[38:39], v[70:71]
	v_pk_mul_f32 v[40:41], v[122:123], v[40:41]
	v_pk_mul_f32 v[40:41], v[24:25], v[40:41]
	v_pk_fma_f32 v[40:41], v[88:89], v[40:41], v[72:73]
	v_cvt_pk_bf16_f32 v126, v38, v39
	v_cvt_pk_bf16_f32 v127, v40, v41
	global_store_dwordx2 v2, v[126:127], s[8:9] offset:1536
	s_add_u32 s8, s8, 0x800
	s_addc_u32 s9, s9, 0
	global_load_dwordx4 v[26:29], v1, s[4:5] nt
	global_load_dwordx4 v[30:33], v1, s[4:5] offset:1024 nt
	global_load_dwordx4 v[34:37], v1, s[4:5] offset:2048 nt
	global_load_dwordx4 v[38:41], v1, s[4:5] offset:3072 nt
	s_add_u32 s4, s4, 0x1000
	s_addc_u32 s5, s5, 0
	s_waitcnt vmcnt(16)
	v_mul_f32_e32 v122, v42, v42
	v_fmac_f32_e32 v122, v43, v43
	v_fmac_f32_e32 v122, v44, v44
	v_fmac_f32_e32 v122, v45, v45
	v_mul_f32_e32 v123, v46, v46
	v_fmac_f32_e32 v123, v47, v47
	v_fmac_f32_e32 v123, v48, v48
	v_fmac_f32_e32 v123, v49, v49
	v_mul_f32_e32 v124, v50, v50
	v_fmac_f32_e32 v124, v51, v51
	v_fmac_f32_e32 v124, v52, v52
	v_fmac_f32_e32 v124, v53, v53
	v_mul_f32_e32 v125, v54, v54
	v_fmac_f32_e32 v125, v55, v55
	v_fmac_f32_e32 v125, v56, v56
	v_fmac_f32_e32 v125, v57, v57
	v_add_f32_e32 v122, v122, v123
	v_add_f32_e32 v124, v124, v125
	v_add_f32_e32 v122, v122, v124
	s_nop 1
	v_add_f32_dpp v122, v122, v122 quad_perm:[1,0,3,2] row_mask:0xf bank_mask:0xf bound_ctrl:1
	s_nop 1
	v_add_f32_dpp v122, v122, v122 quad_perm:[2,3,0,1] row_mask:0xf bank_mask:0xf bound_ctrl:1
	s_nop 1
	v_add_f32_dpp v122, v122, v122 row_half_mirror row_mask:0xf bank_mask:0xf bound_ctrl:1
	s_nop 1
	v_add_f32_dpp v122, v122, v122 row_mirror row_mask:0xf bank_mask:0xf bound_ctrl:1
	v_mov_b32_e32 v123, v122
	s_nop 1
	v_permlane16_swap_b32_e32 v122, v123
	v_add_f32_e32 v122, v122, v123
	v_mov_b32_e32 v123, v122
	s_nop 1
	v_permlane32_swap_b32_e32 v122, v123
	v_add_f32_e32 v122, v122, v123
	v_fmamk_f32 v122, v122, 0x3a800000, v3
	v_rsq_f32_e32 v122, v122
	s_nop 0
	v_mov_b32_e32 v123, v122
	v_pk_mul_f32 v[42:43], v[122:123], v[42:43]
	v_pk_mul_f32 v[42:43], v[10:11], v[42:43]
	v_pk_fma_f32 v[42:43], v[74:75], v[42:43], v[58:59]
	v_pk_mul_f32 v[44:45], v[122:123], v[44:45]
	v_pk_mul_f32 v[44:45], v[12:13], v[44:45]
	v_pk_fma_f32 v[44:45], v[76:77], v[44:45], v[60:61]
	v_cvt_pk_bf16_f32 v124, v42, v43
	v_cvt_pk_bf16_f32 v125, v44, v45
	global_store_dwordx2 v2, v[124:125], s[8:9]
	v_pk_mul_f32 v[46:47], v[122:123], v[46:47]
	v_pk_mul_f32 v[46:47], v[14:15], v[46:47]
	v_pk_fma_f32 v[46:47], v[78:79], v[46:47], v[62:63]
	v_pk_mul_f32 v[48:49], v[122:123], v[48:49]
	v_pk_mul_f32 v[48:49], v[16:17], v[48:49]
	v_pk_fma_f32 v[48:49], v[80:81], v[48:49], v[64:65]
	v_cvt_pk_bf16_f32 v126, v46, v47
	v_cvt_pk_bf16_f32 v127, v48, v49
	global_store_dwordx2 v2, v[126:127], s[8:9] offset:512
	v_pk_mul_f32 v[50:51], v[122:123], v[50:51]
	v_pk_mul_f32 v[50:51], v[18:19], v[50:51]
	v_pk_fma_f32 v[50:51], v[82:83], v[50:51], v[66:67]
	v_pk_mul_f32 v[52:53], v[122:123], v[52:53]
	v_pk_mul_f32 v[52:53], v[20:21], v[52:53]
	v_pk_fma_f32 v[52:53], v[84:85], v[52:53], v[68:69]
	v_cvt_pk_bf16_f32 v124, v50, v51
	v_cvt_pk_bf16_f32 v125, v52, v53
	global_store_dwordx2 v2, v[124:125], s[8:9] offset:1024
	v_pk_mul_f32 v[54:55], v[122:123], v[54:55]
	v_pk_mul_f32 v[54:55], v[22:23], v[54:55]
	v_pk_fma_f32 v[54:55], v[86:87], v[54:55], v[70:71]
	v_pk_mul_f32 v[56:57], v[122:123], v[56:57]
	v_pk_mul_f32 v[56:57], v[24:25], v[56:57]
	v_pk_fma_f32 v[56:57], v[88:89], v[56:57], v[72:73]
	v_cvt_pk_bf16_f32 v126, v54, v55
	v_cvt_pk_bf16_f32 v127, v56, v57
	global_store_dwordx2 v2, v[126:127], s[8:9] offset:1536
	s_add_u32 s8, s8, 0x800
	s_addc_u32 s9, s9, 0
	s_waitcnt vmcnt(12)
	v_mul_f32_e32 v122, v90, v90
	v_fmac_f32_e32 v122, v91, v91
	v_fmac_f32_e32 v122, v92, v92
	v_fmac_f32_e32 v122, v93, v93
	v_mul_f32_e32 v123, v94, v94
	v_fmac_f32_e32 v123, v95, v95
	v_fmac_f32_e32 v123, v96, v96
	v_fmac_f32_e32 v123, v97, v97
	v_mul_f32_e32 v124, v98, v98
	v_fmac_f32_e32 v124, v99, v99
	v_fmac_f32_e32 v124, v100, v100
	v_fmac_f32_e32 v124, v101, v101
	v_mul_f32_e32 v125, v102, v102
	v_fmac_f32_e32 v125, v103, v103
	v_fmac_f32_e32 v125, v104, v104
	v_fmac_f32_e32 v125, v105, v105
	v_add_f32_e32 v122, v122, v123
	v_add_f32_e32 v124, v124, v125
	v_add_f32_e32 v122, v122, v124
	s_nop 1
	v_add_f32_dpp v122, v122, v122 quad_perm:[1,0,3,2] row_mask:0xf bank_mask:0xf bound_ctrl:1
	s_nop 1
	v_add_f32_dpp v122, v122, v122 quad_perm:[2,3,0,1] row_mask:0xf bank_mask:0xf bound_ctrl:1
	s_nop 1
	v_add_f32_dpp v122, v122, v122 row_half_mirror row_mask:0xf bank_mask:0xf bound_ctrl:1
	s_nop 1
	v_add_f32_dpp v122, v122, v122 row_mirror row_mask:0xf bank_mask:0xf bound_ctrl:1
	v_mov_b32_e32 v123, v122
	s_nop 1
	v_permlane16_swap_b32_e32 v122, v123
	v_add_f32_e32 v122, v122, v123
	v_mov_b32_e32 v123, v122
	s_nop 1
	v_permlane32_swap_b32_e32 v122, v123
	v_add_f32_e32 v122, v122, v123
	v_fmamk_f32 v122, v122, 0x3a800000, v3
	v_rsq_f32_e32 v122, v122
	s_nop 0
	v_mov_b32_e32 v123, v122
	v_pk_mul_f32 v[90:91], v[122:123], v[90:91]
	v_pk_mul_f32 v[90:91], v[10:11], v[90:91]
	v_pk_fma_f32 v[90:91], v[74:75], v[90:91], v[58:59]
	v_pk_mul_f32 v[92:93], v[122:123], v[92:93]
	v_pk_mul_f32 v[92:93], v[12:13], v[92:93]
	v_pk_fma_f32 v[92:93], v[76:77], v[92:93], v[60:61]
	v_cvt_pk_bf16_f32 v124, v90, v91
	v_cvt_pk_bf16_f32 v125, v92, v93
	global_store_dwordx2 v2, v[124:125], s[8:9]
	v_pk_mul_f32 v[94:95], v[122:123], v[94:95]
	v_pk_mul_f32 v[94:95], v[14:15], v[94:95]
	v_pk_fma_f32 v[94:95], v[78:79], v[94:95], v[62:63]
	v_pk_mul_f32 v[96:97], v[122:123], v[96:97]
	v_pk_mul_f32 v[96:97], v[16:17], v[96:97]
	v_pk_fma_f32 v[96:97], v[80:81], v[96:97], v[64:65]
	v_cvt_pk_bf16_f32 v126, v94, v95
	v_cvt_pk_bf16_f32 v127, v96, v97
	global_store_dwordx2 v2, v[126:127], s[8:9] offset:512
	v_pk_mul_f32 v[98:99], v[122:123], v[98:99]
	v_pk_mul_f32 v[98:99], v[18:19], v[98:99]
	v_pk_fma_f32 v[98:99], v[82:83], v[98:99], v[66:67]
	v_pk_mul_f32 v[100:101], v[122:123], v[100:101]
	v_pk_mul_f32 v[100:101], v[20:21], v[100:101]
	v_pk_fma_f32 v[100:101], v[84:85], v[100:101], v[68:69]
	v_cvt_pk_bf16_f32 v124, v98, v99
	v_cvt_pk_bf16_f32 v125, v100, v101
	global_store_dwordx2 v2, v[124:125], s[8:9] offset:1024
	v_pk_mul_f32 v[102:103], v[122:123], v[102:103]
	v_pk_mul_f32 v[102:103], v[22:23], v[102:103]
	v_pk_fma_f32 v[102:103], v[86:87], v[102:103], v[70:71]
	v_pk_mul_f32 v[104:105], v[122:123], v[104:105]
	v_pk_mul_f32 v[104:105], v[24:25], v[104:105]
	v_pk_fma_f32 v[104:105], v[88:89], v[104:105], v[72:73]
	v_cvt_pk_bf16_f32 v126, v102, v103
	v_cvt_pk_bf16_f32 v127, v104, v105
	global_store_dwordx2 v2, v[126:127], s[8:9] offset:1536
	s_add_u32 s8, s8, 0x800
	s_addc_u32 s9, s9, 0
	s_waitcnt vmcnt(8)
	v_mul_f32_e32 v122, v26, v26
	v_fmac_f32_e32 v122, v27, v27
	v_fmac_f32_e32 v122, v28, v28
	v_fmac_f32_e32 v122, v29, v29
	v_mul_f32_e32 v123, v30, v30
	v_fmac_f32_e32 v123, v31, v31
	v_fmac_f32_e32 v123, v32, v32
	v_fmac_f32_e32 v123, v33, v33
	v_mul_f32_e32 v124, v34, v34
	v_fmac_f32_e32 v124, v35, v35
	v_fmac_f32_e32 v124, v36, v36
	v_fmac_f32_e32 v124, v37, v37
	v_mul_f32_e32 v125, v38, v38
	v_fmac_f32_e32 v125, v39, v39
	v_fmac_f32_e32 v125, v40, v40
	v_fmac_f32_e32 v125, v41, v41
	v_add_f32_e32 v122, v122, v123
	v_add_f32_e32 v124, v124, v125
	v_add_f32_e32 v122, v122, v124
	s_nop 1
	v_add_f32_dpp v122, v122, v122 quad_perm:[1,0,3,2] row_mask:0xf bank_mask:0xf bound_ctrl:1
	s_nop 1
	v_add_f32_dpp v122, v122, v122 quad_perm:[2,3,0,1] row_mask:0xf bank_mask:0xf bound_ctrl:1
	s_nop 1
	v_add_f32_dpp v122, v122, v122 row_half_mirror row_mask:0xf bank_mask:0xf bound_ctrl:1
	s_nop 1
	v_add_f32_dpp v122, v122, v122 row_mirror row_mask:0xf bank_mask:0xf bound_ctrl:1
	v_mov_b32_e32 v123, v122
	s_nop 1
	v_permlane16_swap_b32_e32 v122, v123
	v_add_f32_e32 v122, v122, v123
	v_mov_b32_e32 v123, v122
	s_nop 1
	v_permlane32_swap_b32_e32 v122, v123
	v_add_f32_e32 v122, v122, v123
	v_fmamk_f32 v122, v122, 0x3a800000, v3
	v_rsq_f32_e32 v122, v122
	s_nop 0
	v_mov_b32_e32 v123, v122
	v_pk_mul_f32 v[26:27], v[122:123], v[26:27]
	v_pk_mul_f32 v[26:27], v[10:11], v[26:27]
	v_pk_fma_f32 v[26:27], v[74:75], v[26:27], v[58:59]
	v_pk_mul_f32 v[28:29], v[122:123], v[28:29]
	v_pk_mul_f32 v[28:29], v[12:13], v[28:29]
	v_pk_fma_f32 v[28:29], v[76:77], v[28:29], v[60:61]
	v_cvt_pk_bf16_f32 v124, v26, v27
	v_cvt_pk_bf16_f32 v125, v28, v29
	global_store_dwordx2 v2, v[124:125], s[8:9]
	v_pk_mul_f32 v[30:31], v[122:123], v[30:31]
	v_pk_mul_f32 v[30:31], v[14:15], v[30:31]
	v_pk_fma_f32 v[30:31], v[78:79], v[30:31], v[62:63]
	v_pk_mul_f32 v[32:33], v[122:123], v[32:33]
	v_pk_mul_f32 v[32:33], v[16:17], v[32:33]
	v_pk_fma_f32 v[32:33], v[80:81], v[32:33], v[64:65]
	v_cvt_pk_bf16_f32 v126, v30, v31
	v_cvt_pk_bf16_f32 v127, v32, v33
	global_store_dwordx2 v2, v[126:127], s[8:9] offset:512
	v_pk_mul_f32 v[34:35], v[122:123], v[34:35]
	v_pk_mul_f32 v[34:35], v[18:19], v[34:35]
	v_pk_fma_f32 v[34:35], v[82:83], v[34:35], v[66:67]
	v_pk_mul_f32 v[36:37], v[122:123], v[36:37]
	v_pk_mul_f32 v[36:37], v[20:21], v[36:37]
	v_pk_fma_f32 v[36:37], v[84:85], v[36:37], v[68:69]
	v_cvt_pk_bf16_f32 v124, v34, v35
	v_cvt_pk_bf16_f32 v125, v36, v37
	global_store_dwordx2 v2, v[124:125], s[8:9] offset:1024
	v_pk_mul_f32 v[38:39], v[122:123], v[38:39]
	v_pk_mul_f32 v[38:39], v[22:23], v[38:39]
	v_pk_fma_f32 v[38:39], v[86:87], v[38:39], v[70:71]
	v_pk_mul_f32 v[40:41], v[122:123], v[40:41]
	v_pk_mul_f32 v[40:41], v[24:25], v[40:41]
	v_pk_fma_f32 v[40:41], v[88:89], v[40:41], v[72:73]
	v_cvt_pk_bf16_f32 v126, v38, v39
	v_cvt_pk_bf16_f32 v127, v40, v41
	global_store_dwordx2 v2, v[126:127], s[8:9] offset:1536
